# s5_gemm A fragments: 4 adjacent lanes per row segment + ds_bpermute lane rotation (16 instead of 64 requests per wave-load), P1 and P3
# speedup vs baseline: 1.0036x; 1.0036x over previous
.LBB0_323:
	s_and_b64 vcc, exec, s[2:3]
	s_cbranch_vccz .LBB0_327
	s_add_i32 s2, s14, 0xfde0
	s_and_b32 s3, s2, 0xffff
	s_mul_i32 s3, s3, 0xf0f1
	s_lshr_b32 s4, s3, 20
	s_mul_i32 s5, s4, 17
	s_sub_i32 s5, s2, s5
	v_mov_b32_e32 v1, v0
	s_and_b32 s6, s5, 0xffff
	s_lshr_b32 s2, s3, 12
	s_and_b32 s3, s2, 0xff00
	s_waitcnt vmcnt(0)
	v_and_b32_e32 v10, 15, v1
	v_and_b32_e32 v2, 0xffffffcf, v1
	s_mul_i32 s2, s4, 0x4400
	s_lshl_b32 s6, s6, 10
	s_lshl_b32 s88, s4, 18
	v_ashrrev_i32_e32 v3, 31, v2
	v_lshlrev_b32_e32 v118, 4, v10
	s_add_i32 s4, s2, s6
	v_lshlrev_b64 v[4:5], 10, v[2:3]
	v_and_b32_e32 v11, 48, v1
	v_or_b32_e32 v8, s4, v118
	v_lshl_or_b32 v3, v8, 5, v11
	v_lshl_add_u64 v[4:5], s[88:89], 0, v[4:5]
	v_or_b32_e32 v130, 0x6000, v3
	v_or_b32_e32 v4, v4, v11
	v_lshl_add_u64 v[70:71], s[86:87], 0, v[130:131]
	v_or_b32_e32 v130, 0x4000, v3
	v_lshl_add_u64 v[78:79], s[86:87], 0, v[4:5]
	v_or_b32_e32 v4, 16, v2
	v_or_b32_e32 v2, 32, v2
	v_lshl_add_u64 v[72:73], s[86:87], 0, v[130:131]
	v_or_b32_e32 v130, 0x2000, v3
	v_ashrrev_i32_e32 v3, 31, v2
	v_or_b32_e32 v6, 48, v1
	v_lshlrev_b64 v[2:3], 10, v[2:3]
	v_ashrrev_i32_e32 v7, 31, v6
	v_lshl_add_u64 v[2:3], s[88:89], 0, v[2:3]
	v_lshlrev_b64 v[6:7], 10, v[6:7]
	v_or_b32_e32 v2, v2, v11
	s_lshl_b32 s4, s5, 19
	v_lshl_add_u64 v[82:83], s[86:87], 0, v[2:3]
	v_lshl_add_u64 v[2:3], s[88:89], 0, v[6:7]
	s_or_b32 s3, s4, s3
	v_lshl_add_u64 v[74:75], s[86:87], 0, v[130:131]
	v_or_b32_e32 v2, v2, v11
	v_lshl_add_u32 v130, v10, 13, s3
	v_lshl_add_u64 v[84:85], s[86:87], 0, v[2:3]
	v_lshlrev_b64 v[2:3], 1, v[130:131]
	v_or_b32_e32 v2, v2, v11
	v_lshl_add_u64 v[86:87], s[86:87], 0, v[2:3]
	v_add_u32_e32 v2, 0x20000, v130
	v_mov_b32_e32 v3, v131
	v_lshlrev_b64 v[2:3], 1, v[2:3]
	v_or_b32_e32 v2, v2, v11
	v_lshl_add_u64 v[88:89], s[86:87], 0, v[2:3]
	v_or_b32_e32 v2, 0x40000, v130
	v_mov_b32_e32 v3, v131
	v_ashrrev_i32_e32 v5, 31, v4
	v_lshlrev_b64 v[2:3], 1, v[2:3]
	v_mov_b32_e32 v9, v131
	v_lshlrev_b64 v[4:5], 10, v[4:5]
	v_or_b32_e32 v2, v2, v11
	v_add_u32_e32 v130, 0x60000, v130
	v_lshlrev_b64 v[8:9], 5, v[8:9]
	v_lshl_add_u64 v[4:5], s[88:89], 0, v[4:5]
	v_lshl_add_u64 v[90:91], s[86:87], 0, v[2:3]
	v_lshlrev_b64 v[2:3], 1, v[130:131]
	v_or_b32_e32 v8, v8, v11
	v_or_b32_e32 v4, v4, v11
	v_or_b32_e32 v2, v2, v11
	v_mov_b32_e32 v18, 0
	v_lshrrev_b32_e32 v119, 4, v1
	v_lshl_add_u64 v[76:77], s[86:87], 0, v[8:9]
	v_lshl_add_u64 v[80:81], s[86:87], 0, v[4:5]
	v_lshl_add_u64 v[92:93], s[86:87], 0, v[2:3]
	v_and_b32_e32 v235, 63, v1
	v_lshrrev_b32_e32 v236, 2, v235
	v_and_b32_e32 v237, 15, v1
	v_sub_u32_e32 v236, v236, v237
	v_lshlrev_b32_e32 v236, 10, v236
	v_and_b32_e32 v238, 3, v235
	v_bfe_u32 v239, v1, 4, 2
	v_sub_u32_e32 v238, v238, v239
	v_lshl_add_u32 v236, v238, 4, v236
	v_lshlrev_b32_e32 v240, 4, v237
	v_lshl_add_u32 v240, v239, 2, v240
	v_ashrrev_i32_e32 v237, 31, v236
	v_lshl_add_u64 v[78:79], v[78:79], 0, v[236:237]
	v_lshl_add_u64 v[80:81], v[80:81], 0, v[236:237]
	v_lshl_add_u64 v[82:83], v[82:83], 0, v[236:237]
	v_lshl_add_u64 v[84:85], v[84:85], 0, v[236:237]
	s_lshr_b32 s62, s88, 18
	s_mul_i32 s64, s62, 0x88000
	s_and_b32 s65, s5, 0xffff
	s_lshl_b32 s65, s65, 15
	s_add_u32 s64, s64, s65
	s_add_u32 s98, s86, s64
	s_addc_u32 s99, s87, 0
	s_add_u32 s98, s98, 0x2bf1100
	s_addc_u32 s99, s99, 0
	s_and_b32 s64, s5, 0xffff
	s_lshl_b32 s64, s64, 20
	s_lshl_b32 s65, s62, 9
	s_add_u32 s64, s64, s65
	s_add_u32 s62, s86, s64
	s_addc_u32 s63, s87, 0
	s_add_u32 s62, s62, 0x80f1100
	s_addc_u32 s63, s63, 0
	v_lshrrev_b32_e32 v226, 6, v1
	v_and_b32_e32 v227, 31, v1
	v_lshlrev_b32_e32 v227, 4, v227
	v_lshl_add_u32 v228, v226, 9, v227
	v_lshl_add_u32 v229, v226, 14, v227
	v_and_b32_e32 v230, 32, v1
	v_cmp_ne_u32_e32 vcc, 0, v230
	v_mov_b32_e32 v231, s98
	v_mov_b32_e32 v232, s99
	v_mov_b32_e32 v233, s62
	v_mov_b32_e32 v234, s63
	v_cndmask_b32_e32 v228, v228, v229, vcc
	v_cndmask_b32_e32 v224, v231, v233, vcc
	v_cndmask_b32_e32 v225, v232, v234, vcc
	v_mov_b32_e32 v229, 0
	v_lshl_add_u64 v[224:225], v[224:225], 0, v[228:229]
	v_mov_b32_e32 v230, 0x800
	v_mov_b32_e32 v231, 0x10000
	v_cndmask_b32_e32 v228, v230, v231, vcc
	v_and_b32_e32 v227, 63, v1
	v_lshlrev_b32_e32 v227, 4, v227
	s_movk_i32 s64, 0x410
	v_mad_u32_u24 v226, v226, s64, v227
	v_and_b32_e32 v222, 15, v1
	v_mul_u32_u24_e32 v222, 0x410, v222
	v_bfe_u32 v227, v1, 4, 2
	v_lshl_add_u32 v222, v227, 4, v222
	global_load_dwordx4 v[2:5], v[224:225], off
	v_lshl_add_u64 v[224:225], v[224:225], 0, v[228:229]
	global_load_dwordx4 v[6:9], v[224:225], off
	v_lshl_add_u64 v[224:225], v[224:225], 0, v[228:229]
	global_load_dwordx4 v[10:13], v[224:225], off
	v_lshl_add_u64 v[224:225], v[224:225], 0, v[228:229]
	global_load_dwordx4 v[14:17], v[224:225], off
	v_lshl_add_u64 v[224:225], v[224:225], 0, v[228:229]
	global_load_dwordx4 v[20:23], v[224:225], off
	v_lshl_add_u64 v[224:225], v[224:225], 0, v[228:229]
	global_load_dwordx4 v[24:27], v[224:225], off
	v_lshl_add_u64 v[224:225], v[224:225], 0, v[228:229]
	global_load_dwordx4 v[28:31], v[224:225], off
	v_lshl_add_u64 v[224:225], v[224:225], 0, v[228:229]
	global_load_dwordx4 v[32:35], v[224:225], off
	v_lshl_add_u64 v[224:225], v[224:225], 0, v[228:229]
	global_load_dwordx4 v[36:39], v[224:225], off
	v_lshl_add_u64 v[224:225], v[224:225], 0, v[228:229]
	global_load_dwordx4 v[40:43], v[224:225], off
	v_lshl_add_u64 v[224:225], v[224:225], 0, v[228:229]
	global_load_dwordx4 v[44:47], v[224:225], off
	v_lshl_add_u64 v[224:225], v[224:225], 0, v[228:229]
	global_load_dwordx4 v[48:51], v[224:225], off
	v_lshl_add_u64 v[224:225], v[224:225], 0, v[228:229]
	global_load_dwordx4 v[52:55], v[224:225], off
	v_lshl_add_u64 v[224:225], v[224:225], 0, v[228:229]
	global_load_dwordx4 v[56:59], v[224:225], off
	v_lshl_add_u64 v[224:225], v[224:225], 0, v[228:229]
	global_load_dwordx4 v[60:63], v[224:225], off
	v_lshl_add_u64 v[224:225], v[224:225], 0, v[228:229]
	global_load_dwordx4 v[64:67], v[224:225], off
	s_waitcnt vmcnt(0)
	ds_write_b128 v226, v[2:5]
	ds_write_b128 v226, v[6:9] offset:4160
	ds_write_b128 v226, v[10:13] offset:8320
	ds_write_b128 v226, v[14:17] offset:12480
	ds_write_b128 v226, v[20:23] offset:16640
	ds_write_b128 v226, v[24:27] offset:20800
	ds_write_b128 v226, v[28:31] offset:24960
	ds_write_b128 v226, v[32:35] offset:29120
	ds_write_b128 v226, v[36:39] offset:33280
	ds_write_b128 v226, v[40:43] offset:37440
	ds_write_b128 v226, v[44:47] offset:41600
	ds_write_b128 v226, v[48:51] offset:45760
	ds_write_b128 v226, v[52:55] offset:49920
	ds_write_b128 v226, v[56:59] offset:54080
	ds_write_b128 v226, v[60:63] offset:58240
	ds_write_b128 v226, v[64:67] offset:62400
	s_waitcnt lgkmcnt(0)
	s_barrier
	s_mov_b32 s3, 0
	s_mov_b64 s[4:5], 0
	v_mov_b32_e32 v19, v18
	v_mov_b32_e32 v20, v18
	v_mov_b32_e32 v21, v18
	v_mov_b32_e32 v22, v18
	v_mov_b32_e32 v23, v18
	v_mov_b32_e32 v24, v18
	v_mov_b32_e32 v25, v18
	v_mov_b32_e32 v26, v18
	v_mov_b32_e32 v27, v18
	v_mov_b32_e32 v28, v18
	v_mov_b32_e32 v29, v18
	v_mov_b32_e32 v30, v18
	v_mov_b32_e32 v31, v18
	v_mov_b32_e32 v32, v18
	v_mov_b32_e32 v33, v18
	v_mov_b32_e32 v34, v18
	v_mov_b32_e32 v35, v18
	v_mov_b32_e32 v36, v18
	v_mov_b32_e32 v37, v18
	v_mov_b32_e32 v38, v18
	v_mov_b32_e32 v39, v18
	v_mov_b32_e32 v40, v18
	v_mov_b32_e32 v41, v18
	v_mov_b32_e32 v42, v18
	v_mov_b32_e32 v43, v18
	v_mov_b32_e32 v44, v18
	v_mov_b32_e32 v45, v18
	v_mov_b32_e32 v46, v18
	v_mov_b32_e32 v47, v18
	v_mov_b32_e32 v48, v18
	v_mov_b32_e32 v49, v18
	v_mov_b32_e32 v50, v18
	v_mov_b32_e32 v51, v18
	v_mov_b32_e32 v52, v18
	v_mov_b32_e32 v53, v18
	v_mov_b32_e32 v54, v18
	v_mov_b32_e32 v55, v18
	v_mov_b32_e32 v56, v18
	v_mov_b32_e32 v57, v18
	v_mov_b32_e32 v58, v18
	v_mov_b32_e32 v59, v18
	v_mov_b32_e32 v60, v18
	v_mov_b32_e32 v61, v18
	v_mov_b32_e32 v62, v18
	v_mov_b32_e32 v63, v18
	v_mov_b32_e32 v64, v18
	v_mov_b32_e32 v65, v18
	v_mov_b32_e32 v14, v18
	v_mov_b32_e32 v15, v18
	v_mov_b32_e32 v16, v18
	v_mov_b32_e32 v17, v18
	v_mov_b32_e32 v10, v18
	v_mov_b32_e32 v11, v18
	v_mov_b32_e32 v12, v18
	v_mov_b32_e32 v13, v18
	v_mov_b32_e32 v6, v18
	v_mov_b32_e32 v7, v18
	v_mov_b32_e32 v8, v18
	v_mov_b32_e32 v9, v18
	v_mov_b32_e32 v2, v18
	v_mov_b32_e32 v3, v18
	v_mov_b32_e32 v4, v18
	v_mov_b32_e32 v5, v18
	s_mov_b64 s[0:1], 0x2bf1100
	s_mov_b32 s7, 0x9b71000
	s_mov_b64 s[8:9], 0x80f0f00
	s_mov_b64 s[10:11], 0x2bf1140
	s_mov_b64 s[16:17], 0x80f0f40
.LBB0_325:
	v_lshl_add_u64 v[158:159], v[78:79], 0, s[4:5]
	v_add_co_u32_e32 v130, vcc, s7, v158
	v_lshl_add_u64 v[162:163], v[80:81], 0, s[4:5]
	s_nop 0
	v_addc_co_u32_e32 v134, vcc, 0, v159, vcc
	v_add_co_u32_e32 v137, vcc, s7, v162
	s_cmp_lt_u32 s3, 8
	s_nop 0
	v_addc_co_u32_e32 v158, vcc, 0, v163, vcc
	v_lshl_add_u64 v[162:163], v[82:83], 0, s[4:5]
	v_add_co_u32_e32 v159, vcc, s7, v162
	v_lshl_add_u64 v[164:165], v[86:87], 0, s[4:5]
	s_nop 0
	v_addc_co_u32_e32 v160, vcc, 0, v163, vcc
	v_lshl_add_u64 v[162:163], v[84:85], 0, s[4:5]
	v_add_co_u32_e32 v166, vcc, s7, v162
	s_nop 1
	v_addc_co_u32_e32 v168, vcc, 0, v163, vcc
	v_lshl_add_u64 v[162:163], v[76:77], 0, s[4:5]
	s_cselect_b64 vcc, -1, 0
	v_lshl_add_u64 v[170:171], v[74:75], 0, s[4:5]
	v_lshl_add_u64 v[174:175], v[88:89], 0, s[4:5]
	v_lshl_add_u64 v[176:177], v[72:73], 0, s[4:5]
	v_lshl_add_u64 v[180:181], v[90:91], 0, s[4:5]
	v_lshl_add_u64 v[182:183], v[70:71], 0, s[4:5]
	v_lshl_add_u64 v[184:185], v[92:93], 0, s[4:5]
	v_lshl_add_u64 v[186:187], v[162:163], 0, s[10:11]
	v_lshl_add_u64 v[162:163], v[164:165], 0, s[16:17]
	v_lshl_add_u64 v[164:165], v[184:185], 0, s[16:17]
	v_cndmask_b32_e32 v169, v163, v187, vcc
	v_cndmask_b32_e32 v172, v162, v186, vcc
	v_mov_b32_e32 v162, v130
	v_mov_b32_e32 v163, v134
	global_load_dwordx4 v[184:187], v[162:163], off offset:320
	v_mov_b32_e32 v162, v137
	v_mov_b32_e32 v163, v158
	global_load_dwordx4 v[188:191], v[162:163], off offset:320
	v_mov_b32_e32 v162, v159
	v_mov_b32_e32 v163, v160
	global_load_dwordx4 v[192:195], v[162:163], off offset:320
	v_mov_b32_e32 v158, v166
	v_mov_b32_e32 v159, v168
	global_load_dwordx4 v[212:215], v[158:159], off offset:320
	v_lshl_add_u64 v[158:159], v[170:171], 0, s[10:11]
	v_lshl_add_u64 v[162:163], v[174:175], 0, s[16:17]
	v_lshl_add_u64 v[170:171], v[176:177], 0, s[10:11]
	v_lshl_add_u64 v[174:175], v[180:181], 0, s[16:17]
	v_lshl_add_u64 v[176:177], v[182:183], 0, s[10:11]
	v_cndmask_b32_e32 v130, v163, v159, vcc
	v_cndmask_b32_e32 v134, v162, v158, vcc
	v_cndmask_b32_e32 v137, v175, v171, vcc
	v_cndmask_b32_e32 v158, v174, v170, vcc
	v_cndmask_b32_e32 v159, v165, v177, vcc
	v_cndmask_b32_e32 v160, v164, v176, vcc
	v_mov_b32_e32 v162, v172
	v_mov_b32_e32 v163, v169
	ds_read_b128 v[174:177], v222 offset:64
	v_mov_b32_e32 v162, v134
	v_mov_b32_e32 v163, v130
	ds_read_b128 v[168:171], v222 offset:16704
	v_mov_b32_e32 v162, v158
	v_mov_b32_e32 v163, v137
	ds_read_b128 v[180:183], v222 offset:33344
	v_mov_b32_e32 v162, v160
	v_mov_b32_e32 v163, v159
	ds_read_b128 v[218:221], v222 offset:49984
	v_lshl_add_u64 v[66:67], v[78:79], 0, s[4:5]
	v_add_co_u32_e32 v116, vcc, s7, v66
	v_lshl_add_u64 v[94:95], v[80:81], 0, s[4:5]
	s_nop 0
	v_addc_co_u32_e32 v117, vcc, 0, v67, vcc
	v_add_co_u32_e32 v114, vcc, s7, v94
	s_cmp_lt_u32 s3, 8
	s_nop 0
	v_addc_co_u32_e32 v115, vcc, 0, v95, vcc
	v_lshl_add_u64 v[94:95], v[82:83], 0, s[4:5]
	v_add_co_u32_e32 v98, vcc, s7, v94
	v_lshl_add_u64 v[96:97], v[86:87], 0, s[4:5]
	s_nop 0
	v_addc_co_u32_e32 v99, vcc, 0, v95, vcc
	v_lshl_add_u64 v[94:95], v[84:85], 0, s[4:5]
	v_add_co_u32_e32 v102, vcc, s7, v94
	v_lshl_add_u64 v[104:105], v[96:97], 0, s[8:9]
	s_nop 0
	v_addc_co_u32_e32 v103, vcc, 0, v95, vcc
	v_lshl_add_u64 v[94:95], v[76:77], 0, s[4:5]
	s_cselect_b64 vcc, -1, 0
	v_lshl_add_u64 v[100:101], v[94:95], 0, s[0:1]
	v_cndmask_b32_e32 v101, v105, v101, vcc
	v_cndmask_b32_e32 v100, v104, v100, vcc
	ds_read_b128 v[142:145], v222
	v_lshl_add_u64 v[100:101], v[74:75], 0, s[4:5]
	v_lshl_add_u64 v[104:105], v[88:89], 0, s[4:5]
	v_lshl_add_u64 v[106:107], v[100:101], 0, s[0:1]
	v_lshl_add_u64 v[108:109], v[104:105], 0, s[8:9]
	v_cndmask_b32_e32 v107, v109, v107, vcc
	v_cndmask_b32_e32 v106, v108, v106, vcc
	ds_read_b128 v[146:149], v222 offset:16640
	v_lshl_add_u64 v[106:107], v[72:73], 0, s[4:5]
	v_lshl_add_u64 v[110:111], v[90:91], 0, s[4:5]
	v_lshl_add_u64 v[108:109], v[106:107], 0, s[0:1]
	v_lshl_add_u64 v[112:113], v[110:111], 0, s[8:9]
	global_load_dwordx4 v[66:69], v[116:117], off offset:256
	global_load_dwordx4 v[120:123], v[114:115], off offset:256
	global_load_dwordx4 v[124:127], v[98:99], off offset:256
	v_cndmask_b32_e32 v109, v113, v109, vcc
	v_cndmask_b32_e32 v108, v112, v108, vcc
	ds_read_b128 v[150:153], v222 offset:33280
	v_lshl_add_u64 v[112:113], v[70:71], 0, s[4:5]
	v_lshl_add_u64 v[108:109], v[92:93], 0, s[4:5]
	v_lshl_add_u64 v[128:129], v[112:113], 0, s[0:1]
	v_lshl_add_u64 v[154:155], v[108:109], 0, s[8:9]
	v_cndmask_b32_e32 v129, v155, v129, vcc
	v_cndmask_b32_e32 v128, v154, v128, vcc
	ds_read_b128 v[154:157], v222 offset:49920
	global_load_dwordx4 v[138:141], v[102:103], off offset:256
	v_lshl_add_u64 v[94:95], v[94:95], 0, s[10:11]
	v_lshl_add_u64 v[96:97], v[96:97], 0, s[16:17]
	v_lshl_add_u64 v[108:109], v[108:109], 0, s[16:17]
	v_cndmask_b32_e32 v95, v97, v95, vcc
	v_cndmask_b32_e32 v94, v96, v94, vcc
	s_add_i32 s3, s3, 2
	s_add_u32 s4, s4, 0x80
	s_addc_u32 s5, s5, 0
	s_cmpk_lg_i32 s4, 0x400
	s_waitcnt vmcnt(0) lgkmcnt(0)
	ds_bpermute_b32 v66, v240, v66
	ds_bpermute_b32 v67, v240, v67
	ds_bpermute_b32 v68, v240, v68
	ds_bpermute_b32 v69, v240, v69
	ds_bpermute_b32 v120, v240, v120
	ds_bpermute_b32 v121, v240, v121
	ds_bpermute_b32 v122, v240, v122
	ds_bpermute_b32 v123, v240, v123
	ds_bpermute_b32 v124, v240, v124
	ds_bpermute_b32 v125, v240, v125
	ds_bpermute_b32 v126, v240, v126
	ds_bpermute_b32 v127, v240, v127
	ds_bpermute_b32 v138, v240, v138
	ds_bpermute_b32 v139, v240, v139
	ds_bpermute_b32 v140, v240, v140
	ds_bpermute_b32 v141, v240, v141
	ds_bpermute_b32 v184, v240, v184
	ds_bpermute_b32 v185, v240, v185
	ds_bpermute_b32 v186, v240, v186
	ds_bpermute_b32 v187, v240, v187
	ds_bpermute_b32 v188, v240, v188
	ds_bpermute_b32 v189, v240, v189
	ds_bpermute_b32 v190, v240, v190
	ds_bpermute_b32 v191, v240, v191
	ds_bpermute_b32 v192, v240, v192
	ds_bpermute_b32 v193, v240, v193
	ds_bpermute_b32 v194, v240, v194
	ds_bpermute_b32 v195, v240, v195
	ds_bpermute_b32 v212, v240, v212
	ds_bpermute_b32 v213, v240, v213
	ds_bpermute_b32 v214, v240, v214
	ds_bpermute_b32 v215, v240, v215
	s_waitcnt lgkmcnt(0)
	v_mfma_f32_16x16x32_bf16 v[62:65], v[66:69], v[142:145], v[62:65]
	v_mfma_f32_16x16x32_bf16 v[58:61], v[66:69], v[146:149], v[58:61]
	s_waitcnt vmcnt(2)
	v_mfma_f32_16x16x32_bf16 v[54:57], v[66:69], v[150:153], v[54:57]
	s_waitcnt vmcnt(1)
	v_mfma_f32_16x16x32_bf16 v[50:53], v[66:69], v[154:157], v[50:53]
	v_mfma_f32_16x16x32_bf16 v[46:49], v[120:123], v[142:145], v[46:49]
	v_mfma_f32_16x16x32_bf16 v[42:45], v[120:123], v[146:149], v[42:45]
	v_mfma_f32_16x16x32_bf16 v[38:41], v[120:123], v[150:153], v[38:41]
	v_mfma_f32_16x16x32_bf16 v[34:37], v[120:123], v[154:157], v[34:37]
	v_mfma_f32_16x16x32_bf16 v[30:33], v[124:127], v[142:145], v[30:33]
	v_mfma_f32_16x16x32_bf16 v[26:29], v[124:127], v[146:149], v[26:29]
	v_mfma_f32_16x16x32_bf16 v[22:25], v[124:127], v[150:153], v[22:25]
	v_mfma_f32_16x16x32_bf16 v[18:21], v[124:127], v[154:157], v[18:21]
	s_nop 0
	s_nop 0
	v_lshl_add_u64 v[98:99], v[100:101], 0, s[10:11]
	v_lshl_add_u64 v[100:101], v[104:105], 0, s[16:17]
	v_lshl_add_u64 v[102:103], v[106:107], 0, s[10:11]
	v_lshl_add_u64 v[104:105], v[110:111], 0, s[16:17]
	v_lshl_add_u64 v[106:107], v[112:113], 0, s[10:11]
	v_cndmask_b32_e32 v99, v101, v99, vcc
	v_cndmask_b32_e32 v98, v100, v98, vcc
	v_cndmask_b32_e32 v103, v105, v103, vcc
	v_cndmask_b32_e32 v102, v104, v102, vcc
	v_cndmask_b32_e32 v107, v109, v107, vcc
	v_cndmask_b32_e32 v106, v108, v106, vcc
	s_waitcnt vmcnt(0)
	v_mfma_f32_16x16x32_bf16 v[14:17], v[138:141], v[142:145], v[14:17]
	s_nop 0
	v_mfma_f32_16x16x32_bf16 v[10:13], v[138:141], v[146:149], v[10:13]
	v_mfma_f32_16x16x32_bf16 v[6:9], v[138:141], v[150:153], v[6:9]
	v_mfma_f32_16x16x32_bf16 v[2:5], v[138:141], v[154:157], v[2:5]
	v_mfma_f32_16x16x32_bf16 v[62:65], v[184:187], v[174:177], v[62:65]
	v_mfma_f32_16x16x32_bf16 v[58:61], v[184:187], v[168:171], v[58:61]
	v_mfma_f32_16x16x32_bf16 v[54:57], v[184:187], v[180:183], v[54:57]
	v_mfma_f32_16x16x32_bf16 v[50:53], v[184:187], v[218:221], v[50:53]
	v_mfma_f32_16x16x32_bf16 v[46:49], v[188:191], v[174:177], v[46:49]
	v_mfma_f32_16x16x32_bf16 v[42:45], v[188:191], v[168:171], v[42:45]
	v_mfma_f32_16x16x32_bf16 v[38:41], v[188:191], v[180:183], v[38:41]
	v_mfma_f32_16x16x32_bf16 v[34:37], v[188:191], v[218:221], v[34:37]
	v_mfma_f32_16x16x32_bf16 v[30:33], v[192:195], v[174:177], v[30:33]
	v_mfma_f32_16x16x32_bf16 v[26:29], v[192:195], v[168:171], v[26:29]
	v_mfma_f32_16x16x32_bf16 v[22:25], v[192:195], v[180:183], v[22:25]
	v_mfma_f32_16x16x32_bf16 v[18:21], v[192:195], v[218:221], v[18:21]
	v_mfma_f32_16x16x32_bf16 v[14:17], v[212:215], v[174:177], v[14:17]
	v_mfma_f32_16x16x32_bf16 v[10:13], v[212:215], v[168:171], v[10:13]
	v_mfma_f32_16x16x32_bf16 v[6:9], v[212:215], v[180:183], v[6:9]
	v_mfma_f32_16x16x32_bf16 v[2:5], v[212:215], v[218:221], v[2:5]
	v_add_u32_e32 v222, 0x80, v222
	s_cbranch_scc1 .LBB0_325
	v_ashrrev_i32_e32 v1, 4, v1
	v_and_b32_e32 v68, -4, v1
	s_mov_b32 s3, s89
	v_ashrrev_i32_e32 v69, 31, v68
	v_lshl_add_u64 v[70:71], s[2:3], 0, v[68:69]
	v_mul_f32_e32 v69, 0x3d372713, v62
	v_mul_f32_e32 v69, v62, v69
	v_fma_f32 v69, v62, v69, v62
	v_mul_f32_e32 v69, 0x3f4c422a, v69
	v_mul_f32_e32 v69, -2.0, v69
	v_mul_f32_e32 v69, 0x3fb8aa3b, v69
	v_exp_f32_e32 v72, v69
	v_mul_f32_e32 v69, 0x3d372713, v63
	v_mul_f32_e32 v69, v63, v69
	v_fma_f32 v69, v63, v69, v63
	v_mul_f32_e32 v69, 0x3f4c422a, v69
	v_mul_f32_e32 v69, -2.0, v69
	v_mul_f32_e32 v69, 0x3fb8aa3b, v69
	v_exp_f32_e32 v73, v69
	v_lshlrev_b32_e32 v66, 3, v119
	v_readlane_b32 s0, v253, 57
	v_and_b32_e32 v130, 24, v66
	v_pk_add_f32 v[72:73], v[72:73], 1.0 op_sel_hi:[1,0]
	v_readlane_b32 s1, v253, 58
	v_div_scale_f32 v69, s[4:5], v73, v73, v63
	v_rcp_f32_e32 v74, v69
	v_lshl_add_u64 v[66:67], s[0:1], 0, v[130:131]
	v_or_b32_e32 v130, s6, v118
	v_fma_f32 v75, -v69, v74, 1.0
	v_fmac_f32_e32 v74, v75, v74
	v_div_scale_f32 v75, vcc, v63, v73, v63
	v_mul_f32_e32 v76, v75, v74
	v_fma_f32 v77, -v69, v76, v75
	v_fmac_f32_e32 v76, v77, v74
	v_fma_f32 v69, -v69, v76, v75
	v_div_fmas_f32 v69, v69, v74, v76
	v_div_fixup_f32 v63, v69, v73, v63
	v_div_scale_f32 v69, s[4:5], v72, v72, v62
	v_rcp_f32_e32 v73, v69
	s_barrier
	v_fma_f32 v74, -v69, v73, 1.0
	v_fmac_f32_e32 v73, v74, v73
	v_div_scale_f32 v74, vcc, v62, v72, v62
	v_mul_f32_e32 v75, v74, v73
	v_fma_f32 v76, -v69, v75, v74
	v_fmac_f32_e32 v75, v76, v73
	v_fma_f32 v69, -v69, v75, v74
	v_div_fmas_f32 v69, v69, v73, v75
	v_div_fixup_f32 v62, v69, v72, v62
	v_cvt_pk_bf16_f32 v62, v62, v63
	v_mul_f32_e32 v63, 0x3d372713, v64
	v_mul_f32_e32 v63, v64, v63
	v_fma_f32 v63, v64, v63, v64
	v_mul_f32_e32 v63, 0x3f4c422a, v63
	v_mul_f32_e32 v63, -2.0, v63
	v_mul_f32_e32 v63, 0x3fb8aa3b, v63
	v_exp_f32_e32 v72, v63
	v_mul_f32_e32 v63, 0x3d372713, v65
	v_mul_f32_e32 v63, v65, v63
	v_fma_f32 v63, v65, v63, v65
	v_mul_f32_e32 v63, 0x3f4c422a, v63
	v_mul_f32_e32 v63, -2.0, v63
	v_mul_f32_e32 v63, 0x3fb8aa3b, v63
	v_exp_f32_e32 v73, v63
	s_nop 0
	v_pk_add_f32 v[72:73], v[72:73], 1.0 op_sel_hi:[1,0]
	s_nop 0
	v_div_scale_f32 v63, s[4:5], v73, v73, v65
	v_rcp_f32_e32 v69, v63
	s_nop 0
	v_fma_f32 v74, -v63, v69, 1.0
	v_fmac_f32_e32 v69, v74, v69
	v_div_scale_f32 v74, vcc, v65, v73, v65
	v_mul_f32_e32 v75, v74, v69
	v_fma_f32 v76, -v63, v75, v74
	v_fmac_f32_e32 v75, v76, v69
	v_fma_f32 v63, -v63, v75, v74
	v_div_fmas_f32 v63, v63, v69, v75
	v_div_fixup_f32 v63, v63, v73, v65
	v_div_scale_f32 v65, s[4:5], v72, v72, v64
	v_rcp_f32_e32 v69, v65
	s_nop 0
	v_fma_f32 v73, -v65, v69, 1.0
	v_fmac_f32_e32 v69, v73, v69
	v_div_scale_f32 v73, vcc, v64, v72, v64
	v_mul_f32_e32 v74, v73, v69
	v_fma_f32 v75, -v65, v74, v73
	v_fmac_f32_e32 v74, v75, v69
	v_fma_f32 v65, -v65, v74, v73
	v_div_fmas_f32 v65, v65, v69, v74
	v_div_fixup_f32 v64, v65, v72, v64
	v_cvt_pk_bf16_f32 v63, v64, v63
	v_lshl_add_u64 v[64:65], v[70:71], 0, v[130:131]
	v_lshlrev_b64 v[64:65], 5, v[64:65]
	v_lshl_add_u64 v[64:65], v[66:67], 0, v[64:65]
	global_store_dwordx2 v[64:65], v[62:63], off
	v_mul_f32_e32 v62, 0x3d372713, v58
	v_mul_f32_e32 v63, 0x3d372713, v59
	v_mul_f32_e32 v62, v58, v62
	v_mul_f32_e32 v63, v59, v63
	v_fma_f32 v62, v58, v62, v58
	v_fma_f32 v63, v59, v63, v59
	v_mul_f32_e32 v62, 0x3f4c422a, v62
	v_mul_f32_e32 v63, 0x3f4c422a, v63
	v_mul_f32_e32 v62, -2.0, v62
	v_mul_f32_e32 v63, -2.0, v63
	v_mul_f32_e32 v62, 0x3fb8aa3b, v62
	v_mul_f32_e32 v63, 0x3fb8aa3b, v63
	v_exp_f32_e32 v62, v62
	v_exp_f32_e32 v63, v63
	s_nop 0
	v_pk_add_f32 v[62:63], v[62:63], 1.0 op_sel_hi:[1,0]
	s_nop 0
	v_div_scale_f32 v64, s[4:5], v63, v63, v59
	v_rcp_f32_e32 v65, v64
	s_nop 0
	v_fma_f32 v69, -v64, v65, 1.0
	v_fmac_f32_e32 v65, v69, v65
	v_div_scale_f32 v69, vcc, v59, v63, v59
	v_mul_f32_e32 v72, v69, v65
	v_fma_f32 v73, -v64, v72, v69
	v_fmac_f32_e32 v72, v73, v65
	v_fma_f32 v64, -v64, v72, v69
	v_div_fmas_f32 v64, v64, v65, v72
	v_div_fixup_f32 v59, v64, v63, v59
	v_div_scale_f32 v63, s[4:5], v62, v62, v58
	v_rcp_f32_e32 v64, v63
	s_nop 0
	v_fma_f32 v65, -v63, v64, 1.0
	v_fmac_f32_e32 v64, v65, v64
	v_div_scale_f32 v65, vcc, v58, v62, v58
	v_mul_f32_e32 v69, v65, v64
	v_fma_f32 v72, -v63, v69, v65
	v_fmac_f32_e32 v69, v72, v64
	v_fma_f32 v63, -v63, v69, v65
	v_div_fmas_f32 v63, v63, v64, v69
	v_div_fixup_f32 v58, v63, v62, v58
	v_cvt_pk_bf16_f32 v62, v58, v59
	v_mul_f32_e32 v58, 0x3d372713, v60
	v_mul_f32_e32 v59, 0x3d372713, v61
	v_mul_f32_e32 v58, v60, v58
	v_mul_f32_e32 v59, v61, v59
	v_fma_f32 v58, v60, v58, v60
	v_fma_f32 v59, v61, v59, v61
	v_mul_f32_e32 v58, 0x3f4c422a, v58
	v_mul_f32_e32 v59, 0x3f4c422a, v59
	v_mul_f32_e32 v58, -2.0, v58
	v_mul_f32_e32 v59, -2.0, v59
	v_mul_f32_e32 v58, 0x3fb8aa3b, v58
	v_mul_f32_e32 v59, 0x3fb8aa3b, v59
	v_exp_f32_e32 v58, v58
	v_exp_f32_e32 v59, v59
	s_nop 0
	v_pk_add_f32 v[58:59], v[58:59], 1.0 op_sel_hi:[1,0]
	s_nop 0
	v_div_scale_f32 v63, s[4:5], v59, v59, v61
	v_rcp_f32_e32 v64, v63
	s_nop 0
	v_fma_f32 v65, -v63, v64, 1.0
	v_fmac_f32_e32 v64, v65, v64
	v_div_scale_f32 v65, vcc, v61, v59, v61
	v_mul_f32_e32 v69, v65, v64
	v_fma_f32 v72, -v63, v69, v65
	v_fmac_f32_e32 v69, v72, v64
	v_fma_f32 v63, -v63, v69, v65
	v_div_fmas_f32 v63, v63, v64, v69
	v_div_fixup_f32 v59, v63, v59, v61
	v_div_scale_f32 v61, s[4:5], v58, v58, v60
	v_rcp_f32_e32 v63, v61
	s_nop 0
	v_fma_f32 v64, -v61, v63, 1.0
	v_fmac_f32_e32 v63, v64, v63
	v_div_scale_f32 v64, vcc, v60, v58, v60
	v_mul_f32_e32 v65, v64, v63
	v_fma_f32 v69, -v61, v65, v64
	v_fmac_f32_e32 v65, v69, v63
	v_fma_f32 v61, -v61, v65, v64
	v_div_fmas_f32 v61, v61, v63, v65
	v_div_fixup_f32 v58, v61, v58, v60
	v_cvt_pk_bf16_f32 v63, v58, v59
	v_or_b32_e32 v58, 0x100, v130
	v_mov_b32_e32 v59, v131
	v_lshl_add_u64 v[60:61], v[70:71], 0, v[58:59]
	v_lshlrev_b64 v[60:61], 5, v[60:61]
	v_lshl_add_u64 v[60:61], v[66:67], 0, v[60:61]
	global_store_dwordx2 v[60:61], v[62:63], off
	v_mul_f32_e32 v60, 0x3d372713, v54
	v_mul_f32_e32 v61, 0x3d372713, v55
	v_mul_f32_e32 v60, v54, v60
	v_mul_f32_e32 v61, v55, v61
	v_fma_f32 v60, v54, v60, v54
	v_fma_f32 v61, v55, v61, v55
	v_mul_f32_e32 v60, 0x3f4c422a, v60
	v_mul_f32_e32 v61, 0x3f4c422a, v61
	v_mul_f32_e32 v60, -2.0, v60
	v_mul_f32_e32 v61, -2.0, v61
	v_mul_f32_e32 v60, 0x3fb8aa3b, v60
	v_mul_f32_e32 v61, 0x3fb8aa3b, v61
	v_exp_f32_e32 v60, v60
	v_exp_f32_e32 v61, v61
	s_nop 0
	v_pk_add_f32 v[60:61], v[60:61], 1.0 op_sel_hi:[1,0]
	s_nop 0
	v_div_scale_f32 v62, s[4:5], v61, v61, v55
	v_rcp_f32_e32 v63, v62
	s_nop 0
	v_fma_f32 v64, -v62, v63, 1.0
	v_fmac_f32_e32 v63, v64, v63
	v_div_scale_f32 v64, vcc, v55, v61, v55
	v_mul_f32_e32 v65, v64, v63
	v_fma_f32 v69, -v62, v65, v64
	v_fmac_f32_e32 v65, v69, v63
	v_fma_f32 v62, -v62, v65, v64
	v_div_fmas_f32 v62, v62, v63, v65
	v_div_fixup_f32 v55, v62, v61, v55
	v_div_scale_f32 v61, s[4:5], v60, v60, v54
	v_rcp_f32_e32 v62, v61
	s_nop 0
	v_fma_f32 v63, -v61, v62, 1.0
	v_fmac_f32_e32 v62, v63, v62
	v_div_scale_f32 v63, vcc, v54, v60, v54
	v_mul_f32_e32 v64, v63, v62
	v_fma_f32 v65, -v61, v64, v63
	v_fmac_f32_e32 v64, v65, v62
	v_fma_f32 v61, -v61, v64, v63
	v_div_fmas_f32 v61, v61, v62, v64
	v_div_fixup_f32 v54, v61, v60, v54
	v_cvt_pk_bf16_f32 v60, v54, v55
	v_mul_f32_e32 v54, 0x3d372713, v56
	v_mul_f32_e32 v55, 0x3d372713, v57
	v_mul_f32_e32 v54, v56, v54
	v_mul_f32_e32 v55, v57, v55
	v_fma_f32 v54, v56, v54, v56
	v_fma_f32 v55, v57, v55, v57
	v_mul_f32_e32 v54, 0x3f4c422a, v54
	v_mul_f32_e32 v55, 0x3f4c422a, v55
	v_mul_f32_e32 v54, -2.0, v54
	v_mul_f32_e32 v55, -2.0, v55
	v_mul_f32_e32 v54, 0x3fb8aa3b, v54
	v_mul_f32_e32 v55, 0x3fb8aa3b, v55
	v_exp_f32_e32 v54, v54
	v_exp_f32_e32 v55, v55
	s_nop 0
	v_pk_add_f32 v[54:55], v[54:55], 1.0 op_sel_hi:[1,0]
	s_nop 0
	v_div_scale_f32 v61, s[4:5], v55, v55, v57
	v_rcp_f32_e32 v62, v61
	s_nop 0
	v_fma_f32 v63, -v61, v62, 1.0
	v_fmac_f32_e32 v62, v63, v62
	v_div_scale_f32 v63, vcc, v57, v55, v57
	v_mul_f32_e32 v64, v63, v62
	v_fma_f32 v65, -v61, v64, v63
	v_fmac_f32_e32 v64, v65, v62
	v_fma_f32 v61, -v61, v64, v63
	v_div_fmas_f32 v61, v61, v62, v64
	v_div_fixup_f32 v55, v61, v55, v57
	v_div_scale_f32 v57, s[4:5], v54, v54, v56
	v_rcp_f32_e32 v61, v57
	s_nop 0
	v_fma_f32 v62, -v57, v61, 1.0
	v_fmac_f32_e32 v61, v62, v61
	v_div_scale_f32 v62, vcc, v56, v54, v56
	v_mul_f32_e32 v63, v62, v61
	v_fma_f32 v64, -v57, v63, v62
	v_fmac_f32_e32 v63, v64, v61
	v_fma_f32 v57, -v57, v63, v62
	v_div_fmas_f32 v57, v57, v61, v63
	v_div_fixup_f32 v54, v57, v54, v56
	v_cvt_pk_bf16_f32 v61, v54, v55
	v_or_b32_e32 v54, 0x200, v130
	v_mov_b32_e32 v55, v131
	v_lshl_add_u64 v[56:57], v[70:71], 0, v[54:55]
	v_lshlrev_b64 v[56:57], 5, v[56:57]
	v_lshl_add_u64 v[56:57], v[66:67], 0, v[56:57]
	global_store_dwordx2 v[56:57], v[60:61], off
	v_mul_f32_e32 v56, 0x3d372713, v50
	v_mul_f32_e32 v57, 0x3d372713, v51
	v_mul_f32_e32 v56, v50, v56
	v_mul_f32_e32 v57, v51, v57
	v_fma_f32 v56, v50, v56, v50
	v_fma_f32 v57, v51, v57, v51
	v_mul_f32_e32 v56, 0x3f4c422a, v56
	v_mul_f32_e32 v57, 0x3f4c422a, v57
	v_mul_f32_e32 v56, -2.0, v56
	v_mul_f32_e32 v57, -2.0, v57
	v_mul_f32_e32 v56, 0x3fb8aa3b, v56
	v_mul_f32_e32 v57, 0x3fb8aa3b, v57
	v_exp_f32_e32 v56, v56
	v_exp_f32_e32 v57, v57
	s_nop 0
	v_pk_add_f32 v[56:57], v[56:57], 1.0 op_sel_hi:[1,0]
	s_nop 0
	v_div_scale_f32 v60, s[4:5], v57, v57, v51
	v_rcp_f32_e32 v61, v60
	s_nop 0
	v_fma_f32 v62, -v60, v61, 1.0
	v_fmac_f32_e32 v61, v62, v61
	v_div_scale_f32 v62, vcc, v51, v57, v51
	v_mul_f32_e32 v63, v62, v61
	v_fma_f32 v64, -v60, v63, v62
	v_fmac_f32_e32 v63, v64, v61
	v_fma_f32 v60, -v60, v63, v62
	v_div_fmas_f32 v60, v60, v61, v63
	v_div_fixup_f32 v51, v60, v57, v51
	v_div_scale_f32 v57, s[4:5], v56, v56, v50
	v_rcp_f32_e32 v60, v57
	s_nop 0
	v_fma_f32 v61, -v57, v60, 1.0
	v_fmac_f32_e32 v60, v61, v60
	v_div_scale_f32 v61, vcc, v50, v56, v50
	v_mul_f32_e32 v62, v61, v60
	v_fma_f32 v63, -v57, v62, v61
	v_fmac_f32_e32 v62, v63, v60
	v_fma_f32 v57, -v57, v62, v61
	v_div_fmas_f32 v57, v57, v60, v62
	v_div_fixup_f32 v50, v57, v56, v50
	v_cvt_pk_bf16_f32 v56, v50, v51
	v_mul_f32_e32 v50, 0x3d372713, v52
	v_mul_f32_e32 v51, 0x3d372713, v53
	v_mul_f32_e32 v50, v52, v50
	v_mul_f32_e32 v51, v53, v51
	v_fma_f32 v50, v52, v50, v52
	v_fma_f32 v51, v53, v51, v53
	v_mul_f32_e32 v50, 0x3f4c422a, v50
	v_mul_f32_e32 v51, 0x3f4c422a, v51
	v_mul_f32_e32 v50, -2.0, v50
	v_mul_f32_e32 v51, -2.0, v51
	v_mul_f32_e32 v50, 0x3fb8aa3b, v50
	v_mul_f32_e32 v51, 0x3fb8aa3b, v51
	v_exp_f32_e32 v50, v50
	v_exp_f32_e32 v51, v51
	s_nop 0
	v_pk_add_f32 v[50:51], v[50:51], 1.0 op_sel_hi:[1,0]
	s_nop 0
	v_div_scale_f32 v57, s[4:5], v51, v51, v53
	v_rcp_f32_e32 v60, v57
	s_nop 0
	v_fma_f32 v61, -v57, v60, 1.0
	v_fmac_f32_e32 v60, v61, v60
	v_div_scale_f32 v61, vcc, v53, v51, v53
	v_mul_f32_e32 v62, v61, v60
	v_fma_f32 v63, -v57, v62, v61
	v_fmac_f32_e32 v62, v63, v60
	v_fma_f32 v57, -v57, v62, v61
	v_div_fmas_f32 v57, v57, v60, v62
	v_div_fixup_f32 v51, v57, v51, v53
	v_div_scale_f32 v53, s[4:5], v50, v50, v52
	v_rcp_f32_e32 v57, v53
	s_nop 0
	v_fma_f32 v60, -v53, v57, 1.0
	v_fmac_f32_e32 v57, v60, v57
	v_div_scale_f32 v60, vcc, v52, v50, v52
	v_mul_f32_e32 v61, v60, v57
	v_fma_f32 v62, -v53, v61, v60
	v_fmac_f32_e32 v61, v62, v57
	v_fma_f32 v53, -v53, v61, v60
	v_div_fmas_f32 v53, v53, v57, v61
	v_div_fixup_f32 v50, v53, v50, v52
	v_cvt_pk_bf16_f32 v57, v50, v51
	v_or_b32_e32 v50, 0x300, v130
	v_mov_b32_e32 v51, v131
	v_lshl_add_u64 v[52:53], v[70:71], 0, v[50:51]
	v_lshlrev_b64 v[52:53], 5, v[52:53]
	v_lshl_add_u64 v[52:53], v[66:67], 0, v[52:53]
	global_store_dwordx2 v[52:53], v[56:57], off
	v_mul_f32_e32 v56, 0x3d372713, v46
	v_mul_f32_e32 v57, 0x3d372713, v47
	v_mul_f32_e32 v56, v46, v56
	v_mul_f32_e32 v57, v47, v57
	v_fma_f32 v56, v46, v56, v46
	v_fma_f32 v57, v47, v57, v47
	v_mul_f32_e32 v56, 0x3f4c422a, v56
	v_mul_f32_e32 v57, 0x3f4c422a, v57
	v_mul_f32_e32 v56, -2.0, v56
	v_mul_f32_e32 v57, -2.0, v57
	v_mul_f32_e32 v56, 0x3fb8aa3b, v56
	v_mul_f32_e32 v57, 0x3fb8aa3b, v57
	v_exp_f32_e32 v56, v56
	v_exp_f32_e32 v57, v57
	v_or_b32_e32 v52, 1, v68
	v_ashrrev_i32_e32 v53, 31, v52
	v_lshl_add_u64 v[52:53], s[2:3], 0, v[52:53]
	v_pk_add_f32 v[56:57], v[56:57], 1.0 op_sel_hi:[1,0]
	s_nop 0
	v_div_scale_f32 v60, s[4:5], v57, v57, v47
	v_rcp_f32_e32 v61, v60
	s_nop 0
	v_fma_f32 v62, -v60, v61, 1.0
	v_fmac_f32_e32 v61, v62, v61
	v_div_scale_f32 v62, vcc, v47, v57, v47
	v_mul_f32_e32 v63, v62, v61
	v_fma_f32 v64, -v60, v63, v62
	v_fmac_f32_e32 v63, v64, v61
	v_fma_f32 v60, -v60, v63, v62
	v_div_fmas_f32 v60, v60, v61, v63
	v_div_fixup_f32 v47, v60, v57, v47
	v_div_scale_f32 v57, s[4:5], v56, v56, v46
	v_rcp_f32_e32 v60, v57
	s_nop 0
	v_fma_f32 v61, -v57, v60, 1.0
	v_fmac_f32_e32 v60, v61, v60
	v_div_scale_f32 v61, vcc, v46, v56, v46
	v_mul_f32_e32 v62, v61, v60
	v_fma_f32 v63, -v57, v62, v61
	v_fmac_f32_e32 v62, v63, v60
	v_fma_f32 v57, -v57, v62, v61
	v_div_fmas_f32 v57, v57, v60, v62
	v_div_fixup_f32 v46, v57, v56, v46
	v_cvt_pk_bf16_f32 v46, v46, v47
	v_mul_f32_e32 v47, 0x3d372713, v48
	v_mul_f32_e32 v47, v48, v47
	v_fma_f32 v47, v48, v47, v48
	v_mul_f32_e32 v47, 0x3f4c422a, v47
	v_mul_f32_e32 v47, -2.0, v47
	v_mul_f32_e32 v47, 0x3fb8aa3b, v47
	v_exp_f32_e32 v56, v47
	v_mul_f32_e32 v47, 0x3d372713, v49
	v_mul_f32_e32 v47, v49, v47
	v_fma_f32 v47, v49, v47, v49
	v_mul_f32_e32 v47, 0x3f4c422a, v47
	v_mul_f32_e32 v47, -2.0, v47
	v_mul_f32_e32 v47, 0x3fb8aa3b, v47
	v_exp_f32_e32 v57, v47
	s_nop 0
	v_pk_add_f32 v[56:57], v[56:57], 1.0 op_sel_hi:[1,0]
	s_nop 0
	v_div_scale_f32 v47, s[4:5], v57, v57, v49
	v_rcp_f32_e32 v60, v47
	s_nop 0
	v_fma_f32 v61, -v47, v60, 1.0
	v_fmac_f32_e32 v60, v61, v60
	v_div_scale_f32 v61, vcc, v49, v57, v49
	v_mul_f32_e32 v62, v61, v60
	v_fma_f32 v63, -v47, v62, v61
	v_fmac_f32_e32 v62, v63, v60
	v_fma_f32 v47, -v47, v62, v61
	v_div_fmas_f32 v47, v47, v60, v62
	v_div_fixup_f32 v47, v47, v57, v49
	v_div_scale_f32 v49, s[4:5], v56, v56, v48
	v_rcp_f32_e32 v57, v49
	s_nop 0
	v_fma_f32 v60, -v49, v57, 1.0
	v_fmac_f32_e32 v57, v60, v57
	v_div_scale_f32 v60, vcc, v48, v56, v48
	v_mul_f32_e32 v61, v60, v57
	v_fma_f32 v62, -v49, v61, v60
	v_fmac_f32_e32 v61, v62, v57
	v_fma_f32 v49, -v49, v61, v60
	v_div_fmas_f32 v49, v49, v57, v61
	v_div_fixup_f32 v48, v49, v56, v48
	v_cvt_pk_bf16_f32 v47, v48, v47
	v_lshl_add_u64 v[48:49], v[52:53], 0, v[130:131]
	v_lshlrev_b64 v[48:49], 5, v[48:49]
	v_lshl_add_u64 v[48:49], v[66:67], 0, v[48:49]
	global_store_dwordx2 v[48:49], v[46:47], off
	v_mul_f32_e32 v46, 0x3d372713, v42
	v_mul_f32_e32 v47, 0x3d372713, v43
	v_mul_f32_e32 v46, v42, v46
	v_mul_f32_e32 v47, v43, v47
	v_fma_f32 v46, v42, v46, v42
	v_fma_f32 v47, v43, v47, v43
	v_mul_f32_e32 v46, 0x3f4c422a, v46
	v_mul_f32_e32 v47, 0x3f4c422a, v47
	v_mul_f32_e32 v46, -2.0, v46
	v_mul_f32_e32 v47, -2.0, v47
	v_mul_f32_e32 v46, 0x3fb8aa3b, v46
	v_mul_f32_e32 v47, 0x3fb8aa3b, v47
	v_exp_f32_e32 v46, v46
	v_exp_f32_e32 v47, v47
	s_nop 0
	v_pk_add_f32 v[46:47], v[46:47], 1.0 op_sel_hi:[1,0]
	s_nop 0
	v_div_scale_f32 v48, s[4:5], v47, v47, v43
	v_rcp_f32_e32 v49, v48
	s_nop 0
	v_fma_f32 v56, -v48, v49, 1.0
	v_fmac_f32_e32 v49, v56, v49
	v_div_scale_f32 v56, vcc, v43, v47, v43
	v_mul_f32_e32 v57, v56, v49
	v_fma_f32 v60, -v48, v57, v56
	v_fmac_f32_e32 v57, v60, v49
	v_fma_f32 v48, -v48, v57, v56
	v_div_fmas_f32 v48, v48, v49, v57
	v_div_fixup_f32 v43, v48, v47, v43
	v_div_scale_f32 v47, s[4:5], v46, v46, v42
	v_rcp_f32_e32 v48, v47
	s_nop 0
	v_fma_f32 v49, -v47, v48, 1.0
	v_fmac_f32_e32 v48, v49, v48
	v_div_scale_f32 v49, vcc, v42, v46, v42
	v_mul_f32_e32 v56, v49, v48
	v_fma_f32 v57, -v47, v56, v49
	v_fmac_f32_e32 v56, v57, v48
	v_fma_f32 v47, -v47, v56, v49
	v_div_fmas_f32 v47, v47, v48, v56
	v_div_fixup_f32 v42, v47, v46, v42
	v_cvt_pk_bf16_f32 v42, v42, v43
	v_mul_f32_e32 v43, 0x3d372713, v44
	v_mul_f32_e32 v43, v44, v43
	v_fma_f32 v43, v44, v43, v44
	v_mul_f32_e32 v43, 0x3f4c422a, v43
	v_mul_f32_e32 v43, -2.0, v43
	v_mul_f32_e32 v43, 0x3fb8aa3b, v43
	v_exp_f32_e32 v46, v43
	v_mul_f32_e32 v43, 0x3d372713, v45
	v_mul_f32_e32 v43, v45, v43
	v_fma_f32 v43, v45, v43, v45
	v_mul_f32_e32 v43, 0x3f4c422a, v43
	v_mul_f32_e32 v43, -2.0, v43
	v_mul_f32_e32 v43, 0x3fb8aa3b, v43
	v_exp_f32_e32 v47, v43
	s_nop 0
	v_pk_add_f32 v[46:47], v[46:47], 1.0 op_sel_hi:[1,0]
	s_nop 0
	v_div_scale_f32 v43, s[4:5], v47, v47, v45
	v_rcp_f32_e32 v48, v43
	s_nop 0
	v_fma_f32 v49, -v43, v48, 1.0
	v_fmac_f32_e32 v48, v49, v48
	v_div_scale_f32 v49, vcc, v45, v47, v45
	v_mul_f32_e32 v56, v49, v48
	v_fma_f32 v57, -v43, v56, v49
	v_fmac_f32_e32 v56, v57, v48
	v_fma_f32 v43, -v43, v56, v49
	v_div_fmas_f32 v43, v43, v48, v56
	v_div_fixup_f32 v43, v43, v47, v45
	v_div_scale_f32 v45, s[4:5], v46, v46, v44
	v_rcp_f32_e32 v47, v45
	s_nop 0
	v_fma_f32 v48, -v45, v47, 1.0
	v_fmac_f32_e32 v47, v48, v47
	v_div_scale_f32 v48, vcc, v44, v46, v44
	v_mul_f32_e32 v49, v48, v47
	v_fma_f32 v56, -v45, v49, v48
	v_fmac_f32_e32 v49, v56, v47
	v_fma_f32 v45, -v45, v49, v48
	v_div_fmas_f32 v45, v45, v47, v49
	v_div_fixup_f32 v44, v45, v46, v44
	v_cvt_pk_bf16_f32 v43, v44, v43
	v_lshl_add_u64 v[44:45], v[52:53], 0, v[58:59]
	v_lshlrev_b64 v[44:45], 5, v[44:45]
	v_lshl_add_u64 v[44:45], v[66:67], 0, v[44:45]
	global_store_dwordx2 v[44:45], v[42:43], off
	v_mul_f32_e32 v42, 0x3d372713, v38
	v_mul_f32_e32 v43, 0x3d372713, v39
	v_mul_f32_e32 v42, v38, v42
	v_mul_f32_e32 v43, v39, v43
	v_fma_f32 v42, v38, v42, v38
	v_fma_f32 v43, v39, v43, v39
	v_mul_f32_e32 v42, 0x3f4c422a, v42
	v_mul_f32_e32 v43, 0x3f4c422a, v43
	v_mul_f32_e32 v42, -2.0, v42
	v_mul_f32_e32 v43, -2.0, v43
	v_mul_f32_e32 v42, 0x3fb8aa3b, v42
	v_mul_f32_e32 v43, 0x3fb8aa3b, v43
	v_exp_f32_e32 v42, v42
	v_exp_f32_e32 v43, v43
	s_nop 0
	v_pk_add_f32 v[42:43], v[42:43], 1.0 op_sel_hi:[1,0]
	s_nop 0
	v_div_scale_f32 v44, s[4:5], v43, v43, v39
	v_rcp_f32_e32 v45, v44
	s_nop 0
	v_fma_f32 v46, -v44, v45, 1.0
	v_fmac_f32_e32 v45, v46, v45
	v_div_scale_f32 v46, vcc, v39, v43, v39
	v_mul_f32_e32 v47, v46, v45
	v_fma_f32 v48, -v44, v47, v46
	v_fmac_f32_e32 v47, v48, v45
	v_fma_f32 v44, -v44, v47, v46
	v_div_fmas_f32 v44, v44, v45, v47
	v_div_fixup_f32 v39, v44, v43, v39
	v_div_scale_f32 v43, s[4:5], v42, v42, v38
	v_rcp_f32_e32 v44, v43
	s_nop 0
	v_fma_f32 v45, -v43, v44, 1.0
	v_fmac_f32_e32 v44, v45, v44
	v_div_scale_f32 v45, vcc, v38, v42, v38
	v_mul_f32_e32 v46, v45, v44
	v_fma_f32 v47, -v43, v46, v45
	v_fmac_f32_e32 v46, v47, v44
	v_fma_f32 v43, -v43, v46, v45
	v_div_fmas_f32 v43, v43, v44, v46
	v_div_fixup_f32 v38, v43, v42, v38
	v_cvt_pk_bf16_f32 v38, v38, v39
	v_mul_f32_e32 v39, 0x3d372713, v40
	v_mul_f32_e32 v39, v40, v39
	v_fma_f32 v39, v40, v39, v40
	v_mul_f32_e32 v39, 0x3f4c422a, v39
	v_mul_f32_e32 v39, -2.0, v39
	v_mul_f32_e32 v39, 0x3fb8aa3b, v39
	v_exp_f32_e32 v42, v39
	v_mul_f32_e32 v39, 0x3d372713, v41
	v_mul_f32_e32 v39, v41, v39
	v_fma_f32 v39, v41, v39, v41
	v_mul_f32_e32 v39, 0x3f4c422a, v39
	v_mul_f32_e32 v39, -2.0, v39
	v_mul_f32_e32 v39, 0x3fb8aa3b, v39
	v_exp_f32_e32 v43, v39
	s_nop 0
	v_pk_add_f32 v[42:43], v[42:43], 1.0 op_sel_hi:[1,0]
	s_nop 0
	v_div_scale_f32 v39, s[4:5], v43, v43, v41
	v_rcp_f32_e32 v44, v39
	s_nop 0
	v_fma_f32 v45, -v39, v44, 1.0
	v_fmac_f32_e32 v44, v45, v44
	v_div_scale_f32 v45, vcc, v41, v43, v41
	v_mul_f32_e32 v46, v45, v44
	v_fma_f32 v47, -v39, v46, v45
	v_fmac_f32_e32 v46, v47, v44
	v_fma_f32 v39, -v39, v46, v45
	v_div_fmas_f32 v39, v39, v44, v46
	v_div_fixup_f32 v39, v39, v43, v41
	v_div_scale_f32 v41, s[4:5], v42, v42, v40
	v_rcp_f32_e32 v43, v41
	s_nop 0
	v_fma_f32 v44, -v41, v43, 1.0
	v_fmac_f32_e32 v43, v44, v43
	v_div_scale_f32 v44, vcc, v40, v42, v40
	v_mul_f32_e32 v45, v44, v43
	v_fma_f32 v46, -v41, v45, v44
	v_fmac_f32_e32 v45, v46, v43
	v_fma_f32 v41, -v41, v45, v44
	v_div_fmas_f32 v41, v41, v43, v45
	v_div_fixup_f32 v40, v41, v42, v40
	v_cvt_pk_bf16_f32 v39, v40, v39
	v_lshl_add_u64 v[40:41], v[52:53], 0, v[54:55]
	v_lshlrev_b64 v[40:41], 5, v[40:41]
	v_lshl_add_u64 v[40:41], v[66:67], 0, v[40:41]
	global_store_dwordx2 v[40:41], v[38:39], off
	v_mul_f32_e32 v38, 0x3d372713, v34
	v_mul_f32_e32 v39, 0x3d372713, v35
	v_mul_f32_e32 v38, v34, v38
	v_mul_f32_e32 v39, v35, v39
	v_fma_f32 v38, v34, v38, v34
	v_fma_f32 v39, v35, v39, v35
	v_mul_f32_e32 v38, 0x3f4c422a, v38
	v_mul_f32_e32 v39, 0x3f4c422a, v39
	v_mul_f32_e32 v38, -2.0, v38
	v_mul_f32_e32 v39, -2.0, v39
	v_mul_f32_e32 v38, 0x3fb8aa3b, v38
	v_mul_f32_e32 v39, 0x3fb8aa3b, v39
	v_exp_f32_e32 v38, v38
	v_exp_f32_e32 v39, v39
	s_nop 0
	v_pk_add_f32 v[38:39], v[38:39], 1.0 op_sel_hi:[1,0]
	s_nop 0
	v_div_scale_f32 v40, s[4:5], v39, v39, v35
	v_rcp_f32_e32 v41, v40
	s_nop 0
	v_fma_f32 v42, -v40, v41, 1.0
	v_fmac_f32_e32 v41, v42, v41
	v_div_scale_f32 v42, vcc, v35, v39, v35
	v_mul_f32_e32 v43, v42, v41
	v_fma_f32 v44, -v40, v43, v42
	v_fmac_f32_e32 v43, v44, v41
	v_fma_f32 v40, -v40, v43, v42
	v_div_fmas_f32 v40, v40, v41, v43
	v_div_fixup_f32 v35, v40, v39, v35
	v_div_scale_f32 v39, s[4:5], v38, v38, v34
	v_rcp_f32_e32 v40, v39
	s_nop 0
	v_fma_f32 v41, -v39, v40, 1.0
	v_fmac_f32_e32 v40, v41, v40
	v_div_scale_f32 v41, vcc, v34, v38, v34
	v_mul_f32_e32 v42, v41, v40
	v_fma_f32 v43, -v39, v42, v41
	v_fmac_f32_e32 v42, v43, v40
	v_fma_f32 v39, -v39, v42, v41
	v_div_fmas_f32 v39, v39, v40, v42
	v_div_fixup_f32 v34, v39, v38, v34
	v_cvt_pk_bf16_f32 v34, v34, v35
	v_mul_f32_e32 v35, 0x3d372713, v36
	v_mul_f32_e32 v35, v36, v35
	v_fma_f32 v35, v36, v35, v36
	v_mul_f32_e32 v35, 0x3f4c422a, v35
	v_mul_f32_e32 v35, -2.0, v35
	v_mul_f32_e32 v35, 0x3fb8aa3b, v35
	v_exp_f32_e32 v38, v35
	v_mul_f32_e32 v35, 0x3d372713, v37
	v_mul_f32_e32 v35, v37, v35
	v_fma_f32 v35, v37, v35, v37
	v_mul_f32_e32 v35, 0x3f4c422a, v35
	v_mul_f32_e32 v35, -2.0, v35
	v_mul_f32_e32 v35, 0x3fb8aa3b, v35
	v_exp_f32_e32 v39, v35
	s_nop 0
	v_pk_add_f32 v[38:39], v[38:39], 1.0 op_sel_hi:[1,0]
	s_nop 0
	v_div_scale_f32 v35, s[4:5], v39, v39, v37
	v_rcp_f32_e32 v40, v35
	s_nop 0
	v_fma_f32 v41, -v35, v40, 1.0
	v_fmac_f32_e32 v40, v41, v40
	v_div_scale_f32 v41, vcc, v37, v39, v37
	v_mul_f32_e32 v42, v41, v40
	v_fma_f32 v43, -v35, v42, v41
	v_fmac_f32_e32 v42, v43, v40
	v_fma_f32 v35, -v35, v42, v41
	v_div_fmas_f32 v35, v35, v40, v42
	v_div_fixup_f32 v35, v35, v39, v37
	v_div_scale_f32 v37, s[4:5], v38, v38, v36
	v_rcp_f32_e32 v39, v37
	s_nop 0
	v_fma_f32 v40, -v37, v39, 1.0
	v_fmac_f32_e32 v39, v40, v39
	v_div_scale_f32 v40, vcc, v36, v38, v36
	v_mul_f32_e32 v41, v40, v39
	v_fma_f32 v42, -v37, v41, v40
	v_fmac_f32_e32 v41, v42, v39
	v_fma_f32 v37, -v37, v41, v40
	v_div_fmas_f32 v37, v37, v39, v41
	v_div_fixup_f32 v36, v37, v38, v36
	v_cvt_pk_bf16_f32 v35, v36, v35
	v_lshl_add_u64 v[36:37], v[52:53], 0, v[50:51]
	v_lshlrev_b64 v[36:37], 5, v[36:37]
	v_lshl_add_u64 v[36:37], v[66:67], 0, v[36:37]
	global_store_dwordx2 v[36:37], v[34:35], off
	v_mul_f32_e32 v36, 0x3d372713, v30
	v_mul_f32_e32 v37, 0x3d372713, v31
	v_mul_f32_e32 v36, v30, v36
	v_mul_f32_e32 v37, v31, v37
	v_fma_f32 v36, v30, v36, v30
	v_fma_f32 v37, v31, v37, v31
	v_mul_f32_e32 v36, 0x3f4c422a, v36
	v_mul_f32_e32 v37, 0x3f4c422a, v37
	v_mul_f32_e32 v36, -2.0, v36
	v_mul_f32_e32 v37, -2.0, v37
	v_mul_f32_e32 v36, 0x3fb8aa3b, v36
	v_mul_f32_e32 v37, 0x3fb8aa3b, v37
	v_exp_f32_e32 v36, v36
	v_exp_f32_e32 v37, v37
	v_or_b32_e32 v34, 2, v68
	v_ashrrev_i32_e32 v35, 31, v34
	v_lshl_add_u64 v[34:35], s[2:3], 0, v[34:35]
	v_pk_add_f32 v[36:37], v[36:37], 1.0 op_sel_hi:[1,0]
	s_nop 0
	v_div_scale_f32 v38, s[4:5], v37, v37, v31
	v_rcp_f32_e32 v39, v38
	s_nop 0
	v_fma_f32 v40, -v38, v39, 1.0
	v_fmac_f32_e32 v39, v40, v39
	v_div_scale_f32 v40, vcc, v31, v37, v31
	v_mul_f32_e32 v41, v40, v39
	v_fma_f32 v42, -v38, v41, v40
	v_fmac_f32_e32 v41, v42, v39
	v_fma_f32 v38, -v38, v41, v40
	v_div_fmas_f32 v38, v38, v39, v41
	v_div_fixup_f32 v31, v38, v37, v31
	v_div_scale_f32 v37, s[4:5], v36, v36, v30
	v_rcp_f32_e32 v38, v37
	s_nop 0
	v_fma_f32 v39, -v37, v38, 1.0
	v_fmac_f32_e32 v38, v39, v38
	v_div_scale_f32 v39, vcc, v30, v36, v30
	v_mul_f32_e32 v40, v39, v38
	v_fma_f32 v41, -v37, v40, v39
	v_fmac_f32_e32 v40, v41, v38
	v_fma_f32 v37, -v37, v40, v39
	v_div_fmas_f32 v37, v37, v38, v40
	v_div_fixup_f32 v30, v37, v36, v30
	v_cvt_pk_bf16_f32 v30, v30, v31
	v_mul_f32_e32 v31, 0x3d372713, v32
	v_mul_f32_e32 v31, v32, v31
	v_fma_f32 v31, v32, v31, v32
	v_mul_f32_e32 v31, 0x3f4c422a, v31
	v_mul_f32_e32 v31, -2.0, v31
	v_mul_f32_e32 v31, 0x3fb8aa3b, v31
	v_exp_f32_e32 v36, v31
	v_mul_f32_e32 v31, 0x3d372713, v33
	v_mul_f32_e32 v31, v33, v31
	v_fma_f32 v31, v33, v31, v33
	v_mul_f32_e32 v31, 0x3f4c422a, v31
	v_mul_f32_e32 v31, -2.0, v31
	v_mul_f32_e32 v31, 0x3fb8aa3b, v31
	v_exp_f32_e32 v37, v31
	s_nop 0
	v_pk_add_f32 v[36:37], v[36:37], 1.0 op_sel_hi:[1,0]
	s_nop 0
	v_div_scale_f32 v31, s[4:5], v37, v37, v33
	v_rcp_f32_e32 v38, v31
	s_nop 0
	v_fma_f32 v39, -v31, v38, 1.0
	v_fmac_f32_e32 v38, v39, v38
	v_div_scale_f32 v39, vcc, v33, v37, v33
	v_mul_f32_e32 v40, v39, v38
	v_fma_f32 v41, -v31, v40, v39
	v_fmac_f32_e32 v40, v41, v38
	v_fma_f32 v31, -v31, v40, v39
	v_div_fmas_f32 v31, v31, v38, v40
	v_div_fixup_f32 v31, v31, v37, v33
	v_div_scale_f32 v33, s[4:5], v36, v36, v32
	v_rcp_f32_e32 v37, v33
	s_nop 0
	v_fma_f32 v38, -v33, v37, 1.0
	v_fmac_f32_e32 v37, v38, v37
	v_div_scale_f32 v38, vcc, v32, v36, v32
	v_mul_f32_e32 v39, v38, v37
	v_fma_f32 v40, -v33, v39, v38
	v_fmac_f32_e32 v39, v40, v37
	v_fma_f32 v33, -v33, v39, v38
	v_div_fmas_f32 v33, v33, v37, v39
	v_div_fixup_f32 v32, v33, v36, v32
	v_cvt_pk_bf16_f32 v31, v32, v31
	v_lshl_add_u64 v[32:33], v[34:35], 0, v[130:131]
	v_lshlrev_b64 v[32:33], 5, v[32:33]
	v_lshl_add_u64 v[32:33], v[66:67], 0, v[32:33]
	global_store_dwordx2 v[32:33], v[30:31], off
	v_mul_f32_e32 v30, 0x3d372713, v26
	v_mul_f32_e32 v31, 0x3d372713, v27
	v_mul_f32_e32 v30, v26, v30
	v_mul_f32_e32 v31, v27, v31
	v_fma_f32 v30, v26, v30, v26
	v_fma_f32 v31, v27, v31, v27
	v_mul_f32_e32 v30, 0x3f4c422a, v30
	v_mul_f32_e32 v31, 0x3f4c422a, v31
	v_mul_f32_e32 v30, -2.0, v30
	v_mul_f32_e32 v31, -2.0, v31
	v_mul_f32_e32 v30, 0x3fb8aa3b, v30
	v_mul_f32_e32 v31, 0x3fb8aa3b, v31
	v_exp_f32_e32 v30, v30
	v_exp_f32_e32 v31, v31
	s_nop 0
	v_pk_add_f32 v[30:31], v[30:31], 1.0 op_sel_hi:[1,0]
	s_nop 0
	v_div_scale_f32 v32, s[4:5], v31, v31, v27
	v_rcp_f32_e32 v33, v32
	s_nop 0
	v_fma_f32 v36, -v32, v33, 1.0
	v_fmac_f32_e32 v33, v36, v33
	v_div_scale_f32 v36, vcc, v27, v31, v27
	v_mul_f32_e32 v37, v36, v33
	v_fma_f32 v38, -v32, v37, v36
	v_fmac_f32_e32 v37, v38, v33
	v_fma_f32 v32, -v32, v37, v36
	v_div_fmas_f32 v32, v32, v33, v37
	v_div_fixup_f32 v27, v32, v31, v27
	v_div_scale_f32 v31, s[4:5], v30, v30, v26
	v_rcp_f32_e32 v32, v31
	s_nop 0
	v_fma_f32 v33, -v31, v32, 1.0
	v_fmac_f32_e32 v32, v33, v32
	v_div_scale_f32 v33, vcc, v26, v30, v26
	v_mul_f32_e32 v36, v33, v32
	v_fma_f32 v37, -v31, v36, v33
	v_fmac_f32_e32 v36, v37, v32
	v_fma_f32 v31, -v31, v36, v33
	v_div_fmas_f32 v31, v31, v32, v36
	v_div_fixup_f32 v26, v31, v30, v26
	v_cvt_pk_bf16_f32 v26, v26, v27
	v_mul_f32_e32 v27, 0x3d372713, v28
	v_mul_f32_e32 v27, v28, v27
	v_fma_f32 v27, v28, v27, v28
	v_mul_f32_e32 v27, 0x3f4c422a, v27
	v_mul_f32_e32 v27, -2.0, v27
	v_mul_f32_e32 v27, 0x3fb8aa3b, v27
	v_exp_f32_e32 v30, v27
	v_mul_f32_e32 v27, 0x3d372713, v29
	v_mul_f32_e32 v27, v29, v27
	v_fma_f32 v27, v29, v27, v29
	v_mul_f32_e32 v27, 0x3f4c422a, v27
	v_mul_f32_e32 v27, -2.0, v27
	v_mul_f32_e32 v27, 0x3fb8aa3b, v27
	v_exp_f32_e32 v31, v27
	s_nop 0
	v_pk_add_f32 v[30:31], v[30:31], 1.0 op_sel_hi:[1,0]
	s_nop 0
	v_div_scale_f32 v27, s[4:5], v31, v31, v29
	v_rcp_f32_e32 v32, v27
	s_nop 0
	v_fma_f32 v33, -v27, v32, 1.0
	v_fmac_f32_e32 v32, v33, v32
	v_div_scale_f32 v33, vcc, v29, v31, v29
	v_mul_f32_e32 v36, v33, v32
	v_fma_f32 v37, -v27, v36, v33
	v_fmac_f32_e32 v36, v37, v32
	v_fma_f32 v27, -v27, v36, v33
	v_div_fmas_f32 v27, v27, v32, v36
	v_div_fixup_f32 v27, v27, v31, v29
	v_div_scale_f32 v29, s[4:5], v30, v30, v28
	v_rcp_f32_e32 v31, v29
	s_nop 0
	v_fma_f32 v32, -v29, v31, 1.0
	v_fmac_f32_e32 v31, v32, v31
	v_div_scale_f32 v32, vcc, v28, v30, v28
	v_mul_f32_e32 v33, v32, v31
	v_fma_f32 v36, -v29, v33, v32
	v_fmac_f32_e32 v33, v36, v31
	v_fma_f32 v29, -v29, v33, v32
	v_div_fmas_f32 v29, v29, v31, v33
	v_div_fixup_f32 v28, v29, v30, v28
	v_cvt_pk_bf16_f32 v27, v28, v27
	v_lshl_add_u64 v[28:29], v[34:35], 0, v[58:59]
	v_lshlrev_b64 v[28:29], 5, v[28:29]
	v_lshl_add_u64 v[28:29], v[66:67], 0, v[28:29]
	global_store_dwordx2 v[28:29], v[26:27], off
	v_mul_f32_e32 v26, 0x3d372713, v22
	v_mul_f32_e32 v27, 0x3d372713, v23
	v_mul_f32_e32 v26, v22, v26
	v_mul_f32_e32 v27, v23, v27
	v_fma_f32 v26, v22, v26, v22
	v_fma_f32 v27, v23, v27, v23
	v_mul_f32_e32 v26, 0x3f4c422a, v26
	v_mul_f32_e32 v27, 0x3f4c422a, v27
	v_mul_f32_e32 v26, -2.0, v26
	v_mul_f32_e32 v27, -2.0, v27
	v_mul_f32_e32 v26, 0x3fb8aa3b, v26
	v_mul_f32_e32 v27, 0x3fb8aa3b, v27
	v_exp_f32_e32 v26, v26
	v_exp_f32_e32 v27, v27
	s_nop 0
	v_pk_add_f32 v[26:27], v[26:27], 1.0 op_sel_hi:[1,0]
	s_nop 0
	v_div_scale_f32 v28, s[4:5], v27, v27, v23
	v_rcp_f32_e32 v29, v28
	s_nop 0
	v_fma_f32 v30, -v28, v29, 1.0
	v_fmac_f32_e32 v29, v30, v29
	v_div_scale_f32 v30, vcc, v23, v27, v23
	v_mul_f32_e32 v31, v30, v29
	v_fma_f32 v32, -v28, v31, v30
	v_fmac_f32_e32 v31, v32, v29
	v_fma_f32 v28, -v28, v31, v30
	v_div_fmas_f32 v28, v28, v29, v31
	v_div_fixup_f32 v23, v28, v27, v23
	v_div_scale_f32 v27, s[4:5], v26, v26, v22
	v_rcp_f32_e32 v28, v27
	s_nop 0
	v_fma_f32 v29, -v27, v28, 1.0
	v_fmac_f32_e32 v28, v29, v28
	v_div_scale_f32 v29, vcc, v22, v26, v22
	v_mul_f32_e32 v30, v29, v28
	v_fma_f32 v31, -v27, v30, v29
	v_fmac_f32_e32 v30, v31, v28
	v_fma_f32 v27, -v27, v30, v29
	v_div_fmas_f32 v27, v27, v28, v30
	v_div_fixup_f32 v22, v27, v26, v22
	v_cvt_pk_bf16_f32 v22, v22, v23
	v_mul_f32_e32 v23, 0x3d372713, v24
	v_mul_f32_e32 v23, v24, v23
	v_fma_f32 v23, v24, v23, v24
	v_mul_f32_e32 v23, 0x3f4c422a, v23
	v_mul_f32_e32 v23, -2.0, v23
	v_mul_f32_e32 v23, 0x3fb8aa3b, v23
	v_exp_f32_e32 v26, v23
	v_mul_f32_e32 v23, 0x3d372713, v25
	v_mul_f32_e32 v23, v25, v23
	v_fma_f32 v23, v25, v23, v25
	v_mul_f32_e32 v23, 0x3f4c422a, v23
	v_mul_f32_e32 v23, -2.0, v23
	v_mul_f32_e32 v23, 0x3fb8aa3b, v23
	v_exp_f32_e32 v27, v23
	s_nop 0
	v_pk_add_f32 v[26:27], v[26:27], 1.0 op_sel_hi:[1,0]
	s_nop 0
	v_div_scale_f32 v23, s[4:5], v27, v27, v25
	v_rcp_f32_e32 v28, v23
	s_nop 0
	v_fma_f32 v29, -v23, v28, 1.0
	v_fmac_f32_e32 v28, v29, v28
	v_div_scale_f32 v29, vcc, v25, v27, v25
	v_mul_f32_e32 v30, v29, v28
	v_fma_f32 v31, -v23, v30, v29
	v_fmac_f32_e32 v30, v31, v28
	v_fma_f32 v23, -v23, v30, v29
	v_div_fmas_f32 v23, v23, v28, v30
	v_div_fixup_f32 v23, v23, v27, v25
	v_div_scale_f32 v25, s[4:5], v26, v26, v24
	v_rcp_f32_e32 v27, v25
	s_nop 0
	v_fma_f32 v28, -v25, v27, 1.0
	v_fmac_f32_e32 v27, v28, v27
	v_div_scale_f32 v28, vcc, v24, v26, v24
	v_mul_f32_e32 v29, v28, v27
	v_fma_f32 v30, -v25, v29, v28
	v_fmac_f32_e32 v29, v30, v27
	v_fma_f32 v25, -v25, v29, v28
	v_div_fmas_f32 v25, v25, v27, v29
	v_div_fixup_f32 v24, v25, v26, v24
	v_cvt_pk_bf16_f32 v23, v24, v23
	v_lshl_add_u64 v[24:25], v[34:35], 0, v[54:55]
	v_lshlrev_b64 v[24:25], 5, v[24:25]
	v_lshl_add_u64 v[24:25], v[66:67], 0, v[24:25]
	global_store_dwordx2 v[24:25], v[22:23], off
	v_mul_f32_e32 v22, 0x3d372713, v18
	v_mul_f32_e32 v23, 0x3d372713, v19
	v_mul_f32_e32 v22, v18, v22
	v_mul_f32_e32 v23, v19, v23
	v_fma_f32 v22, v18, v22, v18
	v_fma_f32 v23, v19, v23, v19
	v_mul_f32_e32 v22, 0x3f4c422a, v22
	v_mul_f32_e32 v23, 0x3f4c422a, v23
	v_mul_f32_e32 v22, -2.0, v22
	v_mul_f32_e32 v23, -2.0, v23
	v_mul_f32_e32 v22, 0x3fb8aa3b, v22
	v_mul_f32_e32 v23, 0x3fb8aa3b, v23
	v_exp_f32_e32 v22, v22
	v_exp_f32_e32 v23, v23
	s_nop 0
	v_pk_add_f32 v[22:23], v[22:23], 1.0 op_sel_hi:[1,0]
	s_nop 0
	v_div_scale_f32 v24, s[4:5], v23, v23, v19
	v_rcp_f32_e32 v25, v24
	s_nop 0
	v_fma_f32 v26, -v24, v25, 1.0
	v_fmac_f32_e32 v25, v26, v25
	v_div_scale_f32 v26, vcc, v19, v23, v19
	v_mul_f32_e32 v27, v26, v25
	v_fma_f32 v28, -v24, v27, v26
	v_fmac_f32_e32 v27, v28, v25
	v_fma_f32 v24, -v24, v27, v26
	v_div_fmas_f32 v24, v24, v25, v27
	v_div_fixup_f32 v19, v24, v23, v19
	v_div_scale_f32 v23, s[4:5], v22, v22, v18
	v_rcp_f32_e32 v24, v23
	s_nop 0
	v_fma_f32 v25, -v23, v24, 1.0
	v_fmac_f32_e32 v24, v25, v24
	v_div_scale_f32 v25, vcc, v18, v22, v18
	v_mul_f32_e32 v26, v25, v24
	v_fma_f32 v27, -v23, v26, v25
	v_fmac_f32_e32 v26, v27, v24
	v_fma_f32 v23, -v23, v26, v25
	v_div_fmas_f32 v23, v23, v24, v26
	v_div_fixup_f32 v18, v23, v22, v18
	v_cvt_pk_bf16_f32 v18, v18, v19
	v_mul_f32_e32 v19, 0x3d372713, v20
	v_mul_f32_e32 v19, v20, v19
	v_fma_f32 v19, v20, v19, v20
	v_mul_f32_e32 v19, 0x3f4c422a, v19
	v_mul_f32_e32 v19, -2.0, v19
	v_mul_f32_e32 v19, 0x3fb8aa3b, v19
	v_exp_f32_e32 v22, v19
	v_mul_f32_e32 v19, 0x3d372713, v21
	v_mul_f32_e32 v19, v21, v19
	v_fma_f32 v19, v21, v19, v21
	v_mul_f32_e32 v19, 0x3f4c422a, v19
	v_mul_f32_e32 v19, -2.0, v19
	v_mul_f32_e32 v19, 0x3fb8aa3b, v19
	v_exp_f32_e32 v23, v19
	s_nop 0
	v_pk_add_f32 v[22:23], v[22:23], 1.0 op_sel_hi:[1,0]
	s_nop 0
	v_div_scale_f32 v19, s[4:5], v23, v23, v21
	v_rcp_f32_e32 v24, v19
	s_nop 0
	v_fma_f32 v25, -v19, v24, 1.0
	v_fmac_f32_e32 v24, v25, v24
	v_div_scale_f32 v25, vcc, v21, v23, v21
	v_mul_f32_e32 v26, v25, v24
	v_fma_f32 v27, -v19, v26, v25
	v_fmac_f32_e32 v26, v27, v24
	v_fma_f32 v19, -v19, v26, v25
	v_div_fmas_f32 v19, v19, v24, v26
	v_div_fixup_f32 v19, v19, v23, v21
	v_div_scale_f32 v21, s[4:5], v22, v22, v20
	v_rcp_f32_e32 v23, v21
	s_nop 0
	v_fma_f32 v24, -v21, v23, 1.0
	v_fmac_f32_e32 v23, v24, v23
	v_div_scale_f32 v24, vcc, v20, v22, v20
	v_mul_f32_e32 v25, v24, v23
	v_fma_f32 v26, -v21, v25, v24
	v_fmac_f32_e32 v25, v26, v23
	v_fma_f32 v21, -v21, v25, v24
	v_div_fmas_f32 v21, v21, v23, v25
	v_div_fixup_f32 v20, v21, v22, v20
	v_cvt_pk_bf16_f32 v19, v20, v19
	v_lshl_add_u64 v[20:21], v[34:35], 0, v[50:51]
	v_lshlrev_b64 v[20:21], 5, v[20:21]
	v_lshl_add_u64 v[20:21], v[66:67], 0, v[20:21]
	global_store_dwordx2 v[20:21], v[18:19], off
	v_or_b32_e32 v18, 3, v1
	v_mul_f32_e32 v1, 0x3d372713, v14
	v_mul_f32_e32 v1, v14, v1
	v_fma_f32 v1, v14, v1, v14
	v_mul_f32_e32 v1, 0x3f4c422a, v1
	v_mul_f32_e32 v1, -2.0, v1
	v_mul_f32_e32 v1, 0x3fb8aa3b, v1
	v_exp_f32_e32 v20, v1
	v_mul_f32_e32 v1, 0x3d372713, v15
	v_mul_f32_e32 v1, v15, v1
	v_fma_f32 v1, v15, v1, v15
	v_mul_f32_e32 v1, 0x3f4c422a, v1
	v_mul_f32_e32 v1, -2.0, v1
	v_mul_f32_e32 v1, 0x3fb8aa3b, v1
	v_exp_f32_e32 v21, v1
	v_ashrrev_i32_e32 v19, 31, v18
	v_lshl_add_u64 v[18:19], s[2:3], 0, v[18:19]
	v_pk_add_f32 v[20:21], v[20:21], 1.0 op_sel_hi:[1,0]
	s_nop 0
	v_div_scale_f32 v1, s[2:3], v21, v21, v15
	v_rcp_f32_e32 v22, v1
	s_nop 0
	v_fma_f32 v23, -v1, v22, 1.0
	v_fmac_f32_e32 v22, v23, v22
	v_div_scale_f32 v23, vcc, v15, v21, v15
	v_mul_f32_e32 v24, v23, v22
	v_fma_f32 v25, -v1, v24, v23
	v_fmac_f32_e32 v24, v25, v22
	v_fma_f32 v1, -v1, v24, v23
	v_div_fmas_f32 v1, v1, v22, v24
	v_div_fixup_f32 v1, v1, v21, v15
	v_div_scale_f32 v15, s[2:3], v20, v20, v14
	v_rcp_f32_e32 v21, v15
	s_nop 0
	v_fma_f32 v22, -v15, v21, 1.0
	v_fmac_f32_e32 v21, v22, v21
	v_div_scale_f32 v22, vcc, v14, v20, v14
	v_mul_f32_e32 v23, v22, v21
	v_fma_f32 v24, -v15, v23, v22
	v_fmac_f32_e32 v23, v24, v21
	v_fma_f32 v15, -v15, v23, v22
	v_div_fmas_f32 v15, v15, v21, v23
	v_div_fixup_f32 v14, v15, v20, v14
	v_cvt_pk_bf16_f32 v14, v14, v1
	v_mul_f32_e32 v1, 0x3d372713, v16
	v_mul_f32_e32 v1, v16, v1
	v_fma_f32 v1, v16, v1, v16
	v_mul_f32_e32 v1, 0x3f4c422a, v1
	v_mul_f32_e32 v1, -2.0, v1
	v_mul_f32_e32 v1, 0x3fb8aa3b, v1
	v_exp_f32_e32 v20, v1
	v_mul_f32_e32 v1, 0x3d372713, v17
	v_mul_f32_e32 v1, v17, v1
	v_fma_f32 v1, v17, v1, v17
	v_mul_f32_e32 v1, 0x3f4c422a, v1
	v_mul_f32_e32 v1, -2.0, v1
	v_mul_f32_e32 v1, 0x3fb8aa3b, v1
	v_exp_f32_e32 v21, v1
	s_nop 0
	v_pk_add_f32 v[20:21], v[20:21], 1.0 op_sel_hi:[1,0]
	s_nop 0
	v_div_scale_f32 v1, s[2:3], v21, v21, v17
	v_rcp_f32_e32 v15, v1
	s_nop 0
	v_fma_f32 v22, -v1, v15, 1.0
	v_fmac_f32_e32 v15, v22, v15
	v_div_scale_f32 v22, vcc, v17, v21, v17
	v_mul_f32_e32 v23, v22, v15
	v_fma_f32 v24, -v1, v23, v22
	v_fmac_f32_e32 v23, v24, v15
	v_fma_f32 v1, -v1, v23, v22
	v_div_fmas_f32 v1, v1, v15, v23
	v_div_scale_f32 v15, s[2:3], v20, v20, v16
	v_div_fixup_f32 v1, v1, v21, v17
	v_rcp_f32_e32 v17, v15
	s_nop 0
	v_fma_f32 v21, -v15, v17, 1.0
	v_fmac_f32_e32 v17, v21, v17
	v_div_scale_f32 v21, vcc, v16, v20, v16
	v_mul_f32_e32 v22, v21, v17
	v_fma_f32 v23, -v15, v22, v21
	v_fmac_f32_e32 v22, v23, v17
	v_fma_f32 v15, -v15, v22, v21
	v_div_fmas_f32 v15, v15, v17, v22
	v_div_fixup_f32 v15, v15, v20, v16
	v_cvt_pk_bf16_f32 v15, v15, v1
	v_mul_f32_e32 v1, 0x3d372713, v10
	v_mul_f32_e32 v1, v10, v1
	v_fma_f32 v1, v10, v1, v10
	v_lshl_add_u64 v[16:17], v[18:19], 0, v[130:131]
	v_mul_f32_e32 v1, 0x3f4c422a, v1
	v_lshlrev_b64 v[16:17], 5, v[16:17]
	v_mul_f32_e32 v1, -2.0, v1
	v_lshl_add_u64 v[16:17], v[66:67], 0, v[16:17]
	v_mul_f32_e32 v1, 0x3fb8aa3b, v1
	global_store_dwordx2 v[16:17], v[14:15], off
	v_exp_f32_e32 v14, v1
	v_mul_f32_e32 v1, 0x3d372713, v11
	v_mul_f32_e32 v1, v11, v1
	v_fma_f32 v1, v11, v1, v11
	v_mul_f32_e32 v1, 0x3f4c422a, v1
	v_mul_f32_e32 v1, -2.0, v1
	v_mul_f32_e32 v1, 0x3fb8aa3b, v1
	v_exp_f32_e32 v15, v1
	s_nop 0
	v_pk_add_f32 v[14:15], v[14:15], 1.0 op_sel_hi:[1,0]
	s_nop 0
	v_div_scale_f32 v1, s[2:3], v15, v15, v11
	v_rcp_f32_e32 v16, v1
	s_nop 0
	v_fma_f32 v17, -v1, v16, 1.0
	v_fmac_f32_e32 v16, v17, v16
	v_div_scale_f32 v17, vcc, v11, v15, v11
	v_mul_f32_e32 v20, v17, v16
	v_fma_f32 v21, -v1, v20, v17
	v_fmac_f32_e32 v20, v21, v16
	v_fma_f32 v1, -v1, v20, v17
	v_div_fmas_f32 v1, v1, v16, v20
	v_div_fixup_f32 v1, v1, v15, v11
	v_div_scale_f32 v11, s[2:3], v14, v14, v10
	v_rcp_f32_e32 v15, v11
	s_nop 0
	v_fma_f32 v16, -v11, v15, 1.0
	v_fmac_f32_e32 v15, v16, v15
	v_div_scale_f32 v16, vcc, v10, v14, v10
	v_mul_f32_e32 v17, v16, v15
	v_fma_f32 v20, -v11, v17, v16
	v_fmac_f32_e32 v17, v20, v15
	v_fma_f32 v11, -v11, v17, v16
	v_div_fmas_f32 v11, v11, v15, v17
	v_div_fixup_f32 v10, v11, v14, v10
	v_cvt_pk_bf16_f32 v10, v10, v1
	v_mul_f32_e32 v1, 0x3d372713, v12
	v_mul_f32_e32 v1, v12, v1
	v_fma_f32 v1, v12, v1, v12
	v_mul_f32_e32 v1, 0x3f4c422a, v1
	v_mul_f32_e32 v1, -2.0, v1
	v_mul_f32_e32 v1, 0x3fb8aa3b, v1
	v_exp_f32_e32 v14, v1
	v_mul_f32_e32 v1, 0x3d372713, v13
	v_mul_f32_e32 v1, v13, v1
	v_fma_f32 v1, v13, v1, v13
	v_mul_f32_e32 v1, 0x3f4c422a, v1
	v_mul_f32_e32 v1, -2.0, v1
	v_mul_f32_e32 v1, 0x3fb8aa3b, v1
	v_exp_f32_e32 v15, v1
	s_nop 0
	v_pk_add_f32 v[14:15], v[14:15], 1.0 op_sel_hi:[1,0]
	s_nop 0
	v_div_scale_f32 v1, s[2:3], v15, v15, v13
	v_rcp_f32_e32 v11, v1
	s_nop 0
	v_fma_f32 v16, -v1, v11, 1.0
	v_fmac_f32_e32 v11, v16, v11
	v_div_scale_f32 v16, vcc, v13, v15, v13
	v_mul_f32_e32 v17, v16, v11
	v_fma_f32 v20, -v1, v17, v16
	v_fmac_f32_e32 v17, v20, v11
	v_fma_f32 v1, -v1, v17, v16
	v_div_fmas_f32 v1, v1, v11, v17
	v_div_scale_f32 v11, s[2:3], v14, v14, v12
	v_div_fixup_f32 v1, v1, v15, v13
	v_rcp_f32_e32 v13, v11
	s_nop 0
	v_fma_f32 v15, -v11, v13, 1.0
	v_fmac_f32_e32 v13, v15, v13
	v_div_scale_f32 v15, vcc, v12, v14, v12
	v_mul_f32_e32 v16, v15, v13
	v_fma_f32 v17, -v11, v16, v15
	v_fmac_f32_e32 v16, v17, v13
	v_fma_f32 v11, -v11, v16, v15
	v_div_fmas_f32 v11, v11, v13, v16
	v_div_fixup_f32 v11, v11, v14, v12
	v_cvt_pk_bf16_f32 v11, v11, v1
	v_mul_f32_e32 v1, 0x3d372713, v6
	v_mul_f32_e32 v1, v6, v1
	v_fma_f32 v1, v6, v1, v6
	v_lshl_add_u64 v[12:13], v[18:19], 0, v[58:59]
	v_mul_f32_e32 v1, 0x3f4c422a, v1
	v_lshlrev_b64 v[12:13], 5, v[12:13]
	v_mul_f32_e32 v1, -2.0, v1
	v_lshl_add_u64 v[12:13], v[66:67], 0, v[12:13]
	v_mul_f32_e32 v1, 0x3fb8aa3b, v1
	global_store_dwordx2 v[12:13], v[10:11], off
	v_exp_f32_e32 v10, v1
	v_mul_f32_e32 v1, 0x3d372713, v7
	v_mul_f32_e32 v1, v7, v1
	v_fma_f32 v1, v7, v1, v7
	v_mul_f32_e32 v1, 0x3f4c422a, v1
	v_mul_f32_e32 v1, -2.0, v1
	v_mul_f32_e32 v1, 0x3fb8aa3b, v1
	v_exp_f32_e32 v11, v1
	s_nop 0
	v_pk_add_f32 v[10:11], v[10:11], 1.0 op_sel_hi:[1,0]
	s_nop 0
	v_div_scale_f32 v1, s[2:3], v11, v11, v7
	v_rcp_f32_e32 v12, v1
	s_nop 0
	v_fma_f32 v13, -v1, v12, 1.0
	v_fmac_f32_e32 v12, v13, v12
	v_div_scale_f32 v13, vcc, v7, v11, v7
	v_mul_f32_e32 v14, v13, v12
	v_fma_f32 v15, -v1, v14, v13
	v_fmac_f32_e32 v14, v15, v12
	v_fma_f32 v1, -v1, v14, v13
	v_div_fmas_f32 v1, v1, v12, v14
	v_div_fixup_f32 v1, v1, v11, v7
	v_div_scale_f32 v7, s[2:3], v10, v10, v6
	v_rcp_f32_e32 v11, v7
	s_nop 0
	v_fma_f32 v12, -v7, v11, 1.0
	v_fmac_f32_e32 v11, v12, v11
	v_div_scale_f32 v12, vcc, v6, v10, v6
	v_mul_f32_e32 v13, v12, v11
	v_fma_f32 v14, -v7, v13, v12
	v_fmac_f32_e32 v13, v14, v11
	v_fma_f32 v7, -v7, v13, v12
	v_div_fmas_f32 v7, v7, v11, v13
	v_div_fixup_f32 v6, v7, v10, v6
	v_cvt_pk_bf16_f32 v6, v6, v1
	v_mul_f32_e32 v1, 0x3d372713, v8
	v_mul_f32_e32 v1, v8, v1
	v_fma_f32 v1, v8, v1, v8
	v_mul_f32_e32 v1, 0x3f4c422a, v1
	v_mul_f32_e32 v1, -2.0, v1
	v_mul_f32_e32 v1, 0x3fb8aa3b, v1
	v_exp_f32_e32 v10, v1
	v_mul_f32_e32 v1, 0x3d372713, v9
	v_mul_f32_e32 v1, v9, v1
	v_fma_f32 v1, v9, v1, v9
	v_mul_f32_e32 v1, 0x3f4c422a, v1
	v_mul_f32_e32 v1, -2.0, v1
	v_mul_f32_e32 v1, 0x3fb8aa3b, v1
	v_exp_f32_e32 v11, v1
	s_nop 0
	v_pk_add_f32 v[10:11], v[10:11], 1.0 op_sel_hi:[1,0]
	s_nop 0
	v_div_scale_f32 v1, s[2:3], v11, v11, v9
	v_rcp_f32_e32 v7, v1
	s_nop 0
	v_fma_f32 v12, -v1, v7, 1.0
	v_fmac_f32_e32 v7, v12, v7
	v_div_scale_f32 v12, vcc, v9, v11, v9
	v_mul_f32_e32 v13, v12, v7
	v_fma_f32 v14, -v1, v13, v12
	v_fmac_f32_e32 v13, v14, v7
	v_fma_f32 v1, -v1, v13, v12
	v_div_fmas_f32 v1, v1, v7, v13
	v_div_scale_f32 v7, s[2:3], v10, v10, v8
	v_div_fixup_f32 v1, v1, v11, v9
	v_rcp_f32_e32 v9, v7
	s_nop 0
	v_fma_f32 v11, -v7, v9, 1.0
	v_fmac_f32_e32 v9, v11, v9
	v_div_scale_f32 v11, vcc, v8, v10, v8
	v_mul_f32_e32 v12, v11, v9
	v_fma_f32 v13, -v7, v12, v11
	v_fmac_f32_e32 v12, v13, v9
	v_fma_f32 v7, -v7, v12, v11
	v_div_fmas_f32 v7, v7, v9, v12
	v_div_fixup_f32 v7, v7, v10, v8
	v_cvt_pk_bf16_f32 v7, v7, v1
	v_mul_f32_e32 v1, 0x3d372713, v2
	v_mul_f32_e32 v1, v2, v1
	v_fma_f32 v1, v2, v1, v2
	v_lshl_add_u64 v[8:9], v[18:19], 0, v[54:55]
	v_mul_f32_e32 v1, 0x3f4c422a, v1
	v_lshlrev_b64 v[8:9], 5, v[8:9]
	v_mul_f32_e32 v1, -2.0, v1
	v_lshl_add_u64 v[8:9], v[66:67], 0, v[8:9]
	v_mul_f32_e32 v1, 0x3fb8aa3b, v1
	global_store_dwordx2 v[8:9], v[6:7], off
	v_exp_f32_e32 v6, v1
	v_mul_f32_e32 v1, 0x3d372713, v3
	v_mul_f32_e32 v1, v3, v1
	v_fma_f32 v1, v3, v1, v3
	v_mul_f32_e32 v1, 0x3f4c422a, v1
	v_mul_f32_e32 v1, -2.0, v1
	v_mul_f32_e32 v1, 0x3fb8aa3b, v1
	v_exp_f32_e32 v7, v1
	s_nop 0
	v_pk_add_f32 v[6:7], v[6:7], 1.0 op_sel_hi:[1,0]
	s_nop 0
	v_div_scale_f32 v1, s[2:3], v7, v7, v3
	v_rcp_f32_e32 v8, v1
	s_nop 0
	v_fma_f32 v9, -v1, v8, 1.0
	v_fmac_f32_e32 v8, v9, v8
	v_div_scale_f32 v9, vcc, v3, v7, v3
	v_mul_f32_e32 v10, v9, v8
	v_fma_f32 v11, -v1, v10, v9
	v_fmac_f32_e32 v10, v11, v8
	v_fma_f32 v1, -v1, v10, v9
	v_div_fmas_f32 v1, v1, v8, v10
	v_div_fixup_f32 v1, v1, v7, v3
	v_div_scale_f32 v3, s[2:3], v6, v6, v2
	v_rcp_f32_e32 v7, v3
	s_nop 0
	v_fma_f32 v8, -v3, v7, 1.0
	v_fmac_f32_e32 v7, v8, v7
	v_div_scale_f32 v8, vcc, v2, v6, v2
	v_mul_f32_e32 v9, v8, v7
	v_fma_f32 v10, -v3, v9, v8
	v_fmac_f32_e32 v9, v10, v7
	v_fma_f32 v3, -v3, v9, v8
	v_div_fmas_f32 v3, v3, v7, v9
	v_div_fixup_f32 v2, v3, v6, v2
	v_cvt_pk_bf16_f32 v2, v2, v1
	v_mul_f32_e32 v1, 0x3d372713, v4
	v_mul_f32_e32 v1, v4, v1
	v_fma_f32 v1, v4, v1, v4
	v_mul_f32_e32 v1, 0x3f4c422a, v1
	v_mul_f32_e32 v1, -2.0, v1
	v_mul_f32_e32 v1, 0x3fb8aa3b, v1
	v_exp_f32_e32 v6, v1
	v_mul_f32_e32 v1, 0x3d372713, v5
	v_mul_f32_e32 v1, v5, v1
	v_fma_f32 v1, v5, v1, v5
	v_mul_f32_e32 v1, 0x3f4c422a, v1
	v_mul_f32_e32 v1, -2.0, v1
	v_mul_f32_e32 v1, 0x3fb8aa3b, v1
	v_exp_f32_e32 v7, v1
	s_nop 0
	v_pk_add_f32 v[6:7], v[6:7], 1.0 op_sel_hi:[1,0]
	s_nop 0
	v_div_scale_f32 v1, s[2:3], v7, v7, v5
	v_rcp_f32_e32 v3, v1
	s_nop 0
	v_fma_f32 v8, -v1, v3, 1.0
	v_fmac_f32_e32 v3, v8, v3
	v_div_scale_f32 v8, vcc, v5, v7, v5
	v_mul_f32_e32 v9, v8, v3
	v_fma_f32 v10, -v1, v9, v8
	v_fmac_f32_e32 v9, v10, v3
	v_fma_f32 v1, -v1, v9, v8
	v_div_fmas_f32 v1, v1, v3, v9
	v_div_scale_f32 v3, s[2:3], v6, v6, v4
	v_div_fixup_f32 v1, v1, v7, v5
	v_rcp_f32_e32 v5, v3
	s_nop 0
	v_fma_f32 v7, -v3, v5, 1.0
	v_fmac_f32_e32 v5, v7, v5
	v_div_scale_f32 v7, vcc, v4, v6, v4
	v_mul_f32_e32 v8, v7, v5
	v_fma_f32 v9, -v3, v8, v7
	v_fmac_f32_e32 v8, v9, v5
	v_fma_f32 v3, -v3, v8, v7
	v_div_fmas_f32 v3, v3, v5, v8
	v_div_fixup_f32 v3, v3, v6, v4
	v_lshl_add_u64 v[4:5], v[18:19], 0, v[50:51]
	v_lshlrev_b64 v[4:5], 5, v[4:5]
	v_cvt_pk_bf16_f32 v3, v3, v1
	v_lshl_add_u64 v[4:5], v[66:67], 0, v[4:5]
	global_store_dwordx2 v[4:5], v[2:3], off
	s_barrier

.LBB0_535:
	s_and_b64 vcc, exec, s[0:1]
	s_cbranch_vccz .LBB0_539
	s_add_i32 s88, s88, 0xf800
	s_sext_i32_i16 s0, s88
	s_mulk_i32 s0, 0x7879
	s_lshr_b32 s1, s0, 31
	s_ashr_i32 s0, s0, 19
	s_add_i32 s2, s0, s1
	v_mov_b32_e32 v1, v0
	s_mul_i32 s0, s2, 17
	s_sub_i32 s3, s88, s0
	s_waitcnt vmcnt(0)
	v_and_b32_e32 v2, 0xffffffcf, v1
	v_and_b32_e32 v85, 15, v1
	v_ashrrev_i32_e32 v3, 31, v2
	s_sext_i32_i16 s4, s3
	v_lshlrev_b64 v[4:5], 9, v[2:3]
	v_lshlrev_b32_e32 v3, 4, v85
	v_lshl_or_b32 v8, s4, 10, v3
	v_or_b32_e32 v10, 0x300, v8
	v_ashrrev_i32_e32 v11, 31, v10
	v_lshlrev_b64 v[10:11], 5, v[10:11]
	s_sext_i32_i16 s5, s2
	v_mov_b32_e32 v3, 0x88000
	s_bfe_i64 s[0:1], s[2:3], 0x100000
	v_mad_i64_i32 v[10:11], s[2:3], s5, v3, v[10:11]
	v_and_b32_e32 v12, 48, v1
	v_or_b32_e32 v10, v10, v12
	v_lshl_add_u64 v[66:67], s[86:87], 0, v[10:11]
	v_or_b32_e32 v10, 0x200, v8
	v_ashrrev_i32_e32 v11, 31, v10
	v_lshlrev_b64 v[10:11], 5, v[10:11]
	v_mad_i64_i32 v[10:11], s[2:3], s5, v3, v[10:11]
	s_lshl_b64 s[6:7], s[0:1], 17
	v_or_b32_e32 v10, v10, v12
	v_lshl_add_u64 v[68:69], s[86:87], 0, v[10:11]
	v_or_b32_e32 v10, 0x100, v8
	v_lshl_add_u64 v[4:5], s[6:7], 0, v[4:5]
	v_ashrrev_i32_e32 v11, 31, v10
	v_ashrrev_i32_e32 v9, 31, v8
	v_or_b32_e32 v4, v4, v12
	v_lshlrev_b64 v[10:11], 5, v[10:11]
	v_lshlrev_b64 v[8:9], 5, v[8:9]
	v_lshl_add_u64 v[74:75], s[86:87], 0, v[4:5]
	v_or_b32_e32 v4, 16, v2
	v_or_b32_e32 v2, 32, v2
	v_mad_i64_i32 v[10:11], s[2:3], s5, v3, v[10:11]
	v_mad_i64_i32 v[8:9], s[2:3], s5, v3, v[8:9]
	v_ashrrev_i32_e32 v3, 31, v2
	v_or_b32_e32 v6, 48, v1
	v_lshlrev_b64 v[2:3], 9, v[2:3]
	v_ashrrev_i32_e32 v7, 31, v6
	v_lshl_add_u64 v[2:3], s[6:7], 0, v[2:3]
	v_lshlrev_b64 v[6:7], 9, v[6:7]
	v_ashrrev_i32_e32 v5, 31, v4
	v_or_b32_e32 v2, v2, v12
	v_lshlrev_b64 v[4:5], 9, v[4:5]
	v_lshl_add_u64 v[78:79], s[86:87], 0, v[2:3]
	v_lshl_add_u64 v[2:3], s[6:7], 0, v[6:7]
	v_lshl_add_u64 v[4:5], s[6:7], 0, v[4:5]
	v_or_b32_e32 v2, v2, v12
	v_or_b32_e32 v10, v10, v12
	v_or_b32_e32 v8, v8, v12
	v_or_b32_e32 v4, v4, v12
	v_lshl_add_u64 v[80:81], s[86:87], 0, v[2:3]
	v_mov_b32_e32 v2, 0
	v_lshrrev_b32_e32 v84, 4, v1
	v_lshl_add_u64 v[70:71], s[86:87], 0, v[10:11]
	v_lshl_add_u64 v[72:73], s[86:87], 0, v[8:9]
	v_lshl_add_u64 v[76:77], s[86:87], 0, v[4:5]
	v_and_b32_e32 v232, 63, v1
	v_lshrrev_b32_e32 v233, 2, v232
	v_and_b32_e32 v234, 15, v1
	v_sub_u32_e32 v233, v233, v234
	v_lshlrev_b32_e32 v233, 9, v233
	v_and_b32_e32 v235, 3, v232
	v_bfe_u32 v236, v1, 4, 2
	v_sub_u32_e32 v235, v235, v236
	v_lshl_add_u32 v233, v235, 4, v233
	v_lshlrev_b32_e32 v238, 4, v234
	v_lshl_add_u32 v238, v236, 2, v238
	v_mov_b32_e32 v232, v233
	v_ashrrev_i32_e32 v233, 31, v232
	v_lshl_add_u64 v[74:75], v[74:75], 0, v[232:233]
	v_lshl_add_u64 v[76:77], v[76:77], 0, v[232:233]
	v_lshl_add_u64 v[78:79], v[78:79], 0, v[232:233]
	v_lshl_add_u64 v[80:81], v[80:81], 0, v[232:233]
	s_mul_i32 s64, s5, 0x88000
	s_lshl_b32 s65, s4, 15
	s_add_u32 s64, s64, s65
	s_add_u32 s62, s86, s64
	s_addc_u32 s63, s87, 0
	s_add_u32 s62, s62, 0x2bf1100
	s_addc_u32 s63, s63, 0
	v_lshlrev_b32_e32 v230, 4, v1
	v_lshrrev_b32_e32 v229, 5, v1
	v_mul_u32_u24_e32 v229, 0x210, v229
	v_and_b32_e32 v231, 31, v1
	v_lshl_add_u32 v229, v231, 4, v229
	v_and_b32_e32 v228, 15, v1
	v_mul_u32_u24_e32 v228, 0x210, v228
	v_bfe_u32 v231, v1, 4, 2
	v_lshl_add_u32 v228, v231, 4, v228
	global_load_dwordx4 v[14:17], v230, s[62:63]
	v_add_u32_e32 v230, 0x1000, v230
	global_load_dwordx4 v[18:21], v230, s[62:63]
	v_add_u32_e32 v230, 0x1000, v230
	global_load_dwordx4 v[22:25], v230, s[62:63]
	v_add_u32_e32 v230, 0x1000, v230
	global_load_dwordx4 v[26:29], v230, s[62:63]
	v_add_u32_e32 v230, 0x1000, v230
	global_load_dwordx4 v[30:33], v230, s[62:63]
	v_add_u32_e32 v230, 0x1000, v230
	global_load_dwordx4 v[34:37], v230, s[62:63]
	v_add_u32_e32 v230, 0x1000, v230
	global_load_dwordx4 v[38:41], v230, s[62:63]
	v_add_u32_e32 v230, 0x1000, v230
	global_load_dwordx4 v[42:45], v230, s[62:63]
	s_waitcnt vmcnt(0)
	ds_write_b128 v229, v[14:17]
	ds_write_b128 v229, v[18:21] offset:4224
	ds_write_b128 v229, v[22:25] offset:8448
	ds_write_b128 v229, v[26:29] offset:12672
	ds_write_b128 v229, v[30:33] offset:16896
	ds_write_b128 v229, v[34:37] offset:21120
	ds_write_b128 v229, v[38:41] offset:25344
	ds_write_b128 v229, v[42:45] offset:29568
	s_waitcnt lgkmcnt(0)
	s_barrier
	s_mov_b64 s[2:3], 0
	v_mov_b32_e32 v3, v2
	v_mov_b32_e32 v4, v2
	v_mov_b32_e32 v5, v2
	v_mov_b32_e32 v6, v2
	v_mov_b32_e32 v7, v2
	v_mov_b32_e32 v8, v2
	v_mov_b32_e32 v9, v2
	v_mov_b32_e32 v10, v2
	v_mov_b32_e32 v11, v2
	v_mov_b32_e32 v12, v2
	v_mov_b32_e32 v13, v2
	v_mov_b32_e32 v38, v2
	v_mov_b32_e32 v39, v2
	v_mov_b32_e32 v40, v2
	v_mov_b32_e32 v41, v2
	v_mov_b32_e32 v50, v2
	v_mov_b32_e32 v51, v2
	v_mov_b32_e32 v52, v2
	v_mov_b32_e32 v53, v2
	v_mov_b32_e32 v54, v2
	v_mov_b32_e32 v55, v2
	v_mov_b32_e32 v56, v2
	v_mov_b32_e32 v57, v2
	v_mov_b32_e32 v58, v2
	v_mov_b32_e32 v59, v2
	v_mov_b32_e32 v60, v2
	v_mov_b32_e32 v61, v2
	v_mov_b32_e32 v62, v2
	v_mov_b32_e32 v63, v2
	v_mov_b32_e32 v64, v2
	v_mov_b32_e32 v65, v2
	v_mov_b32_e32 v46, v2
	v_mov_b32_e32 v47, v2
	v_mov_b32_e32 v48, v2
	v_mov_b32_e32 v49, v2
	v_mov_b32_e32 v42, v2
	v_mov_b32_e32 v43, v2
	v_mov_b32_e32 v44, v2
	v_mov_b32_e32 v45, v2
	v_mov_b32_e32 v34, v2
	v_mov_b32_e32 v35, v2
	v_mov_b32_e32 v36, v2
	v_mov_b32_e32 v37, v2
	v_mov_b32_e32 v26, v2
	v_mov_b32_e32 v27, v2
	v_mov_b32_e32 v28, v2
	v_mov_b32_e32 v29, v2
	v_mov_b32_e32 v30, v2
	v_mov_b32_e32 v31, v2
	v_mov_b32_e32 v32, v2
	v_mov_b32_e32 v33, v2
	v_mov_b32_e32 v22, v2
	v_mov_b32_e32 v23, v2
	v_mov_b32_e32 v24, v2
	v_mov_b32_e32 v25, v2
	v_mov_b32_e32 v18, v2
	v_mov_b32_e32 v19, v2
	v_mov_b32_e32 v20, v2
	v_mov_b32_e32 v21, v2
	v_mov_b32_e32 v14, v2
	v_mov_b32_e32 v15, v2
	v_mov_b32_e32 v16, v2
	v_mov_b32_e32 v17, v2
	s_mov_b32 s5, 0x9771000
	s_mov_b32 s6, 0x2bf1000
.LBB0_537:
	v_lshl_add_u64 v[140:141], v[74:75], 0, s[2:3]
	v_add_co_u32_e32 v130, vcc, s5, v140
	v_lshl_add_u64 v[142:143], v[76:77], 0, s[2:3]
	s_nop 0
	v_addc_co_u32_e32 v134, vcc, 0, v141, vcc
	v_add_co_u32_e32 v137, vcc, s5, v142
	v_lshl_add_u64 v[140:141], v[78:79], 0, s[2:3]
	s_nop 0
	v_addc_co_u32_e32 v144, vcc, 0, v143, vcc
	v_add_co_u32_e32 v142, vcc, s5, v140
	v_lshl_add_u64 v[146:147], v[80:81], 0, s[2:3]
	s_nop 0
	v_addc_co_u32_e32 v143, vcc, 0, v141, vcc
	v_add_co_u32_e32 v140, vcc, s5, v146
	v_lshl_add_u64 v[148:149], v[72:73], 0, s[2:3]
	s_nop 0
	v_addc_co_u32_e32 v141, vcc, 0, v147, vcc
	v_add_co_u32_e32 v145, vcc, s6, v148
	v_lshl_add_u64 v[146:147], v[70:71], 0, s[2:3]
	s_nop 0
	v_addc_co_u32_e32 v150, vcc, 0, v149, vcc
	v_add_co_u32_e32 v148, vcc, s6, v146
	v_lshl_add_u64 v[152:153], v[68:69], 0, s[2:3]
	s_nop 0
	v_addc_co_u32_e32 v149, vcc, 0, v147, vcc
	v_add_co_u32_e32 v146, vcc, s6, v152
	v_lshl_add_u64 v[154:155], v[66:67], 0, s[2:3]
	s_nop 0
	v_addc_co_u32_e32 v147, vcc, 0, v153, vcc
	v_add_co_u32_e32 v151, vcc, s6, v154
	s_nop 1
	v_addc_co_u32_e32 v152, vcc, 0, v155, vcc
	v_mov_b32_e32 v154, v130
	v_mov_b32_e32 v155, v134
	global_load_dwordx4 v[156:159], v[154:155], off offset:320
	v_mov_b32_e32 v154, v137
	v_mov_b32_e32 v155, v144
	global_load_dwordx4 v[162:165], v[154:155], off offset:320
	global_load_dwordx4 v[168:171], v[142:143], off offset:320
	global_load_dwordx4 v[174:177], v[140:141], off offset:320
	v_mov_b32_e32 v140, v145
	v_mov_b32_e32 v141, v150
	ds_read_b128 v[180:183], v228 offset:64
	ds_read_b128 v[140:143], v228 offset:8512
	ds_read_b128 v[184:187], v228 offset:16960
	v_mov_b32_e32 v144, v151
	v_mov_b32_e32 v145, v152
	ds_read_b128 v[146:149], v228 offset:25408
	v_lshl_add_u64 v[82:83], v[74:75], 0, s[2:3]
	v_add_co_u32_e32 v82, vcc, s5, v82
	v_lshl_add_u64 v[90:91], v[76:77], 0, s[2:3]
	s_nop 0
	v_addc_co_u32_e32 v83, vcc, 0, v83, vcc
	v_add_co_u32_e32 v118, vcc, s5, v90
	v_lshl_add_u64 v[94:95], v[78:79], 0, s[2:3]
	s_nop 0
	v_addc_co_u32_e32 v119, vcc, 0, v91, vcc
	v_add_co_u32_e32 v120, vcc, s5, v94
	v_lshl_add_u64 v[98:99], v[80:81], 0, s[2:3]
	s_nop 0
	v_addc_co_u32_e32 v121, vcc, 0, v95, vcc
	v_add_co_u32_e32 v122, vcc, s5, v98
	v_lshl_add_u64 v[102:103], v[72:73], 0, s[2:3]
	s_nop 0
	v_addc_co_u32_e32 v123, vcc, 0, v99, vcc
	v_add_co_u32_e32 v124, vcc, s6, v102
	v_lshl_add_u64 v[106:107], v[70:71], 0, s[2:3]
	s_nop 0
	v_addc_co_u32_e32 v125, vcc, 0, v103, vcc
	v_add_co_u32_e32 v126, vcc, s6, v106
	v_lshl_add_u64 v[110:111], v[68:69], 0, s[2:3]
	s_nop 0
	v_addc_co_u32_e32 v127, vcc, 0, v107, vcc
	global_load_dwordx4 v[86:89], v[82:83], off offset:256
	global_load_dwordx4 v[90:93], v[118:119], off offset:256
	global_load_dwordx4 v[94:97], v[120:121], off offset:256
	global_load_dwordx4 v[98:101], v[122:123], off offset:256
	v_add_co_u32_e32 v128, vcc, s6, v110
	v_lshl_add_u64 v[114:115], v[66:67], 0, s[2:3]
	s_nop 0
	v_addc_co_u32_e32 v129, vcc, 0, v111, vcc
	v_add_co_u32_e32 v138, vcc, s6, v114
	ds_read_b128 v[102:105], v228
	ds_read_b128 v[106:109], v228 offset:8448
	v_addc_co_u32_e32 v139, vcc, 0, v115, vcc
	ds_read_b128 v[110:113], v228 offset:16896
	ds_read_b128 v[114:117], v228 offset:25344
	s_add_u32 s2, s2, 0x80
	s_addc_u32 s3, s3, 0
	s_cmpk_lg_i32 s2, 0x200
	s_waitcnt vmcnt(0) lgkmcnt(0)
	ds_bpermute_b32 v86, v238, v86
	ds_bpermute_b32 v87, v238, v87
	ds_bpermute_b32 v88, v238, v88
	ds_bpermute_b32 v89, v238, v89
	ds_bpermute_b32 v90, v238, v90
	ds_bpermute_b32 v91, v238, v91
	ds_bpermute_b32 v92, v238, v92
	ds_bpermute_b32 v93, v238, v93
	ds_bpermute_b32 v94, v238, v94
	ds_bpermute_b32 v95, v238, v95
	ds_bpermute_b32 v96, v238, v96
	ds_bpermute_b32 v97, v238, v97
	ds_bpermute_b32 v98, v238, v98
	ds_bpermute_b32 v99, v238, v99
	ds_bpermute_b32 v100, v238, v100
	ds_bpermute_b32 v101, v238, v101
	ds_bpermute_b32 v156, v238, v156
	ds_bpermute_b32 v157, v238, v157
	ds_bpermute_b32 v158, v238, v158
	ds_bpermute_b32 v159, v238, v159
	ds_bpermute_b32 v162, v238, v162
	ds_bpermute_b32 v163, v238, v163
	ds_bpermute_b32 v164, v238, v164
	ds_bpermute_b32 v165, v238, v165
	ds_bpermute_b32 v168, v238, v168
	ds_bpermute_b32 v169, v238, v169
	ds_bpermute_b32 v170, v238, v170
	ds_bpermute_b32 v171, v238, v171
	ds_bpermute_b32 v174, v238, v174
	ds_bpermute_b32 v175, v238, v175
	ds_bpermute_b32 v176, v238, v176
	ds_bpermute_b32 v177, v238, v177
	s_waitcnt lgkmcnt(0)
	v_mfma_f32_16x16x32_bf16 v[62:65], v[86:89], v[102:105], v[62:65]
	s_waitcnt vmcnt(2)
	v_mfma_f32_16x16x32_bf16 v[58:61], v[86:89], v[106:109], v[58:61]
	s_waitcnt vmcnt(1)
	v_mfma_f32_16x16x32_bf16 v[54:57], v[86:89], v[110:113], v[54:57]
	s_waitcnt vmcnt(0)
	v_mfma_f32_16x16x32_bf16 v[50:53], v[86:89], v[114:117], v[50:53]
	v_mfma_f32_16x16x32_bf16 v[38:41], v[90:93], v[102:105], v[38:41]
	v_mfma_f32_16x16x32_bf16 v[10:13], v[90:93], v[106:109], v[10:13]
	v_mfma_f32_16x16x32_bf16 v[6:9], v[90:93], v[110:113], v[6:9]
	v_mfma_f32_16x16x32_bf16 v[2:5], v[90:93], v[114:117], v[2:5]
	v_mfma_f32_16x16x32_bf16 v[46:49], v[94:97], v[102:105], v[46:49]
	v_mfma_f32_16x16x32_bf16 v[42:45], v[94:97], v[106:109], v[42:45]
	v_mfma_f32_16x16x32_bf16 v[34:37], v[94:97], v[110:113], v[34:37]
	v_mfma_f32_16x16x32_bf16 v[26:29], v[94:97], v[114:117], v[26:29]
	v_mfma_f32_16x16x32_bf16 v[30:33], v[98:101], v[102:105], v[30:33]
	v_mfma_f32_16x16x32_bf16 v[22:25], v[98:101], v[106:109], v[22:25]
	v_mfma_f32_16x16x32_bf16 v[18:21], v[98:101], v[110:113], v[18:21]
	v_mfma_f32_16x16x32_bf16 v[14:17], v[98:101], v[114:117], v[14:17]
	s_waitcnt vmcnt(0)
	v_mfma_f32_16x16x32_bf16 v[62:65], v[156:159], v[180:183], v[62:65]
	v_mfma_f32_16x16x32_bf16 v[58:61], v[156:159], v[140:143], v[58:61]
	v_mfma_f32_16x16x32_bf16 v[54:57], v[156:159], v[184:187], v[54:57]
	v_mfma_f32_16x16x32_bf16 v[50:53], v[156:159], v[146:149], v[50:53]
	v_mfma_f32_16x16x32_bf16 v[38:41], v[162:165], v[180:183], v[38:41]
	v_mfma_f32_16x16x32_bf16 v[10:13], v[162:165], v[140:143], v[10:13]
	v_mfma_f32_16x16x32_bf16 v[6:9], v[162:165], v[184:187], v[6:9]
	v_mfma_f32_16x16x32_bf16 v[2:5], v[162:165], v[146:149], v[2:5]
	v_mfma_f32_16x16x32_bf16 v[46:49], v[168:171], v[180:183], v[46:49]
	v_mfma_f32_16x16x32_bf16 v[42:45], v[168:171], v[140:143], v[42:45]
	v_mfma_f32_16x16x32_bf16 v[34:37], v[168:171], v[184:187], v[34:37]
	v_mfma_f32_16x16x32_bf16 v[26:29], v[168:171], v[146:149], v[26:29]
	v_mfma_f32_16x16x32_bf16 v[30:33], v[174:177], v[180:183], v[30:33]
	v_mfma_f32_16x16x32_bf16 v[22:25], v[174:177], v[140:143], v[22:25]
	v_mfma_f32_16x16x32_bf16 v[18:21], v[174:177], v[184:187], v[18:21]
	v_mfma_f32_16x16x32_bf16 v[14:17], v[174:177], v[146:149], v[14:17]
	v_add_u32_e32 v228, 0x80, v228
	s_cbranch_scc1 .LBB0_537
	v_and_b32_e32 v66, 3, v84
	v_and_b32_e32 v1, 0xffffffc0, v1
	s_lshl_b64 s[0:1], s[0:1], 9
	v_readlane_b32 s2, v254, 9
	v_lshl_or_b32 v66, v66, 2, v1
	v_lshl_or_b32 v68, s4, 6, v85
	v_readlane_b32 s3, v254, 10
	s_add_u32 s0, s2, s0
	s_addc_u32 s1, s3, s1
	v_ashrrev_i32_e32 v67, 31, v66
	v_ashrrev_i32_e32 v69, 31, v68
	v_lshl_add_u64 v[66:67], v[66:67], 1, s[0:1]
	v_cvt_pk_bf16_f32 v62, v62, v63
	v_cvt_pk_bf16_f32 v63, v64, v65
	v_lshlrev_b64 v[64:65], 14, v[68:69]
	v_lshl_add_u64 v[64:65], v[66:67], 0, v[64:65]
	global_store_dwordx2 v[64:65], v[62:63], off
	v_or_b32_e32 v62, 16, v68
	v_ashrrev_i32_e32 v63, 31, v62
	v_cvt_pk_bf16_f32 v58, v58, v59
	v_cvt_pk_bf16_f32 v59, v60, v61
	v_lshlrev_b64 v[60:61], 14, v[62:63]
	v_lshl_add_u64 v[60:61], v[66:67], 0, v[60:61]
	global_store_dwordx2 v[60:61], v[58:59], off
	v_or_b32_e32 v58, 32, v68
	v_ashrrev_i32_e32 v59, 31, v58
	v_cvt_pk_bf16_f32 v54, v54, v55
	v_cvt_pk_bf16_f32 v55, v56, v57
	v_lshlrev_b64 v[56:57], 14, v[58:59]
	v_lshl_add_u64 v[56:57], v[66:67], 0, v[56:57]
	global_store_dwordx2 v[56:57], v[54:55], off
	v_or_b32_e32 v54, 48, v68
	v_ashrrev_i32_e32 v55, 31, v54
	v_cvt_pk_bf16_f32 v50, v50, v51
	v_cvt_pk_bf16_f32 v51, v52, v53
	v_lshlrev_b64 v[52:53], 14, v[54:55]
	v_lshl_add_u64 v[52:53], v[66:67], 0, v[52:53]
	v_cvt_pk_bf16_f32 v2, v2, v3
	v_cvt_pk_bf16_f32 v3, v4, v5
	global_store_dwordx2 v[52:53], v[2:3], off offset:32
	v_cvt_pk_bf16_f32 v2, v46, v47
	v_cvt_pk_bf16_f32 v3, v48, v49
	global_store_dwordx2 v[64:65], v[2:3], off offset:64
	v_cvt_pk_bf16_f32 v2, v42, v43
	v_cvt_pk_bf16_f32 v3, v44, v45
	global_store_dwordx2 v[60:61], v[2:3], off offset:64
	v_cvt_pk_bf16_f32 v2, v34, v35
	v_cvt_pk_bf16_f32 v3, v36, v37
	global_store_dwordx2 v[56:57], v[2:3], off offset:64
	v_cvt_pk_bf16_f32 v2, v26, v27
	v_cvt_pk_bf16_f32 v3, v28, v29
	global_store_dwordx2 v[52:53], v[2:3], off offset:64
	v_cvt_pk_bf16_f32 v2, v30, v31
	v_cvt_pk_bf16_f32 v3, v32, v33
	global_store_dwordx2 v[64:65], v[2:3], off offset:96
	v_cvt_pk_bf16_f32 v2, v22, v23
	v_cvt_pk_bf16_f32 v3, v24, v25
	global_store_dwordx2 v[60:61], v[2:3], off offset:96
	v_cvt_pk_bf16_f32 v2, v18, v19
	v_cvt_pk_bf16_f32 v3, v20, v21
	v_cvt_pk_bf16_f32 v38, v38, v39
	v_cvt_pk_bf16_f32 v39, v40, v41
	v_cvt_pk_bf16_f32 v10, v10, v11
	v_cvt_pk_bf16_f32 v11, v12, v13
	v_cvt_pk_bf16_f32 v6, v6, v7
	v_cvt_pk_bf16_f32 v7, v8, v9
	global_store_dwordx2 v[56:57], v[2:3], off offset:96
	v_cvt_pk_bf16_f32 v2, v14, v15
	v_cvt_pk_bf16_f32 v3, v16, v17
	global_store_dwordx2 v[52:53], v[50:51], off
	global_store_dwordx2 v[64:65], v[38:39], off offset:32
	global_store_dwordx2 v[60:61], v[10:11], off offset:32
	global_store_dwordx2 v[56:57], v[6:7], off offset:32
	global_store_dwordx2 v[52:53], v[2:3], off offset:96
